# P.V MFMAs ordered ks-outer (packed-P operand fixed over four independent accumulators)
# baseline (speedup 1.0000x reference)
; __device__ __forceinline__ void finishSM(f32x16& p0, f32x16& p1, float alpha, float& l_reg, bf16x8& pa0, bf16x8& pa1, bf16x8& pa2, bf16x8& pa3) {
; #pragma unroll
;   for (int r = 0; r < 16; ++r) p1[r] = __builtin_amdgcn_exp2f(p1[r]);
;   float ps = 0;
; #pragma unroll
;   for (int r = 0; r < 16; ++r) ps += p0[r];
; #pragma unroll
;   for (int r = 0; r < 16; ++r) ps += p1[r];
;   { auto rr = __builtin_amdgcn_permlane32_swap(__float_as_uint(ps), __float_as_uint(ps), false, false);
;     ps = __uint_as_float(rr[0]) + __uint_as_float(rr[1]); }
;   l_reg = l_reg * alpha + ps;
;     ...
;   PK4(p0, 0, pa0); PK4(p0, 8, pa1); PK4(p1, 0, pa2); PK4(p1, 8, pa3);
;     ...
; }
; __device__ __forceinline__ void qkt(f32x16& p0, f32x16& p1, const bf16* Ks, const bf16x8* qr, int r32, int hi) {
;   p0 = f32x16{}; p1 = f32x16{};
; #pragma unroll
;   for (int d0 = 0; d0 < 8; ++d0) { int cb = (d0 * 16 + hi * 8) * 2;
;     bf16x8 b0 = *reinterpret_cast<const bf16x8*>((const char*)Ks + KSWZ(r32, cb));
;     bf16x8 b1 = *reinterpret_cast<const bf16x8*>((const char*)Ks + KSWZ(32 + r32, cb));
;     p0 = __builtin_amdgcn_mfma_f32_32x32x16_bf16(b0, qr[d0], p0, 0, 0, 0);
;     p1 = __builtin_amdgcn_mfma_f32_32x32x16_bf16(b1, qr[d0], p1, 0, 0, 0); }
; }
; __device__ __forceinline__ int v_st(int k, int c) { const int kk = (k & ~0xC) | ((k & 4) << 1) | ((k & 8) >> 1); return ((kk >> 3) * 4 + (c >> 5)) * 512 + ((kk & 7) * 32 + (c & 31)) * 2; }
; __device__ __forceinline__ int v_rd_base(int lane) { return ((lane & 3) << 3) | (((lane >> 2) & 3) << 6) | (((lane >> 4) & 1) << 5) | (((lane >> 5) & 1) << 8); }
; template <int OFF> __device__ __forceinline__ s16x4 tr_read(int vb) {
;   s16x4 r; asm volatile("ds_read_b64_tr_b16 %0, %1 offset:%2" : "=&v"(r) : "v"(vb), "i"(OFF) : "memory"); return r;
; }
; template <int D0> __device__ __forceinline__ void pv_one(f32x16& od, int vb, bf16x8 pa0, bf16x8 pa1, bf16x8 pa2, bf16x8 pa3) {
;   const s16x4 l0 = tr_read<v_rd_off(D0, 0, 0)>(vb), h0 = tr_read<v_rd_off(D0, 0, 1)>(vb), l1 = tr_read<v_rd_off(D0, 1, 0)>(vb), h1 = tr_read<v_rd_off(D0, 1, 1)>(vb);
;   const s16x4 l2 = tr_read<v_rd_off(D0, 2, 0)>(vb), h2 = tr_read<v_rd_off(D0, 2, 1)>(vb), l3 = tr_read<v_rd_off(D0, 3, 0)>(vb), h3 = tr_read<v_rd_off(D0, 3, 1)>(vb);
;   asm volatile("s_waitcnt lgkmcnt(0)" ::: "memory"); SBAR();
;     ...
;   od = __builtin_amdgcn_mfma_f32_32x32x16_bf16(pa0, PK(l0, h0), od, 0, 0, 0);
.Lprio_done:
.Ldense_loop:
	s_waitcnt lgkmcnt(7)
	v_mfma_f32_32x32x16_bf16 v[128:143], v[200:203], v[124:127], 0
	ds_read_b128 v[200:203], v176 offset:16384
	v_cvt_pk_bf16_f32 v184, v64, v65
	v_add_f32_e32 v169, v169, v64
	v_add_f32_e32 v219, v219, v65
	global_load_dwordx4 v[246:249], v183, s[98:99]
	s_waitcnt lgkmcnt(7)
	v_mfma_f32_32x32x16_bf16 v[144:159], v[204:207], v[124:127], 0
	ds_read_b128 v[204:207], v176 offset:24576
	v_cvt_pk_bf16_f32 v185, v66, v67
	v_add_f32_e32 v222, v222, v66
	v_add_f32_e32 v254, v254, v67
	s_waitcnt lgkmcnt(7)
	v_mfma_f32_32x32x16_bf16 v[128:143], v[208:211], v[120:123], v[128:143]
	ds_read_b128 v[208:211], v177 offset:16384
	v_cvt_pk_bf16_f32 v186, v68, v69
	v_add_f32_e32 v169, v169, v68
	v_add_f32_e32 v219, v219, v69
	global_load_dwordx4 v[250:253], v183, s[100:101]
	s_add_u32 s98, s98, 0x150000
	s_addc_u32 s99, s99, 0
	s_add_u32 s100, s100, 0x150000
	s_addc_u32 s101, s101, 0
	s_waitcnt lgkmcnt(7)
	v_mfma_f32_32x32x16_bf16 v[144:159], v[212:215], v[120:123], v[144:159]
	ds_read_b128 v[212:215], v177 offset:24576
	v_cvt_pk_bf16_f32 v187, v70, v71
	v_add_f32_e32 v222, v222, v70
	v_add_f32_e32 v254, v254, v71
	s_waitcnt lgkmcnt(7)
	v_mfma_f32_32x32x16_bf16 v[128:143], v[230:233], v[116:119], v[128:143]
	ds_read_b128 v[230:233], v178 offset:16384
	v_cvt_pk_bf16_f32 v188, v72, v73
	v_add_f32_e32 v169, v169, v72
	v_add_f32_e32 v219, v219, v73
	v_permlane32_swap_b32_e32 v184, v186
	global_load_dwordx4 v[164:167], v183, s[0:1] offset:512
	s_waitcnt lgkmcnt(7)
	v_mfma_f32_32x32x16_bf16 v[144:159], v[234:237], v[116:119], v[144:159]
	ds_read_b128 v[234:237], v178 offset:24576
	v_cvt_pk_bf16_f32 v189, v74, v75
	v_add_f32_e32 v222, v222, v74
	v_add_f32_e32 v254, v254, v75
	v_permlane32_swap_b32_e32 v185, v187
	s_waitcnt lgkmcnt(7)
	v_mfma_f32_32x32x16_bf16 v[128:143], v[238:241], v[112:115], v[128:143]
	ds_read_b128 v[238:241], v179 offset:16384
	v_cvt_pk_bf16_f32 v190, v76, v77
	v_add_f32_e32 v169, v169, v76
	v_add_f32_e32 v219, v219, v77
	global_load_dwordx4 v[160:163], v183, s[4:5] offset:512
	s_add_u32 s0, s0, 0x150000
	s_addc_u32 s1, s1, 0
	s_add_u32 s4, s4, 0x150000
	s_addc_u32 s5, s5, 0
	s_waitcnt lgkmcnt(7)
	v_mfma_f32_32x32x16_bf16 v[144:159], v[242:245], v[112:115], v[144:159]
	ds_read_b128 v[242:245], v179 offset:24576
	v_cvt_pk_bf16_f32 v191, v78, v79
	v_add_f32_e32 v222, v222, v78
	v_add_f32_e32 v254, v254, v79
	s_waitcnt lgkmcnt(7)
	v_mfma_f32_32x32x16_bf16 v[128:143], v[200:203], v[108:111], v[128:143]
	v_cvt_pk_bf16_f32 v192, v80, v81
	v_add_f32_e32 v169, v169, v80
	v_add_f32_e32 v219, v219, v81
	v_permlane32_swap_b32_e32 v188, v190
	s_waitcnt lgkmcnt(6)
	v_mfma_f32_32x32x16_bf16 v[144:159], v[204:207], v[108:111], v[144:159]
	v_cvt_pk_bf16_f32 v193, v82, v83
	v_add_f32_e32 v222, v222, v82
	v_add_f32_e32 v254, v254, v83
	v_permlane32_swap_b32_e32 v189, v191
	s_waitcnt lgkmcnt(5)
	v_mfma_f32_32x32x16_bf16 v[128:143], v[208:211], v[104:107], v[128:143]
	v_cvt_pk_bf16_f32 v194, v84, v85
	v_add_f32_e32 v169, v169, v84
	v_add_f32_e32 v219, v219, v85
	s_waitcnt lgkmcnt(4)
	v_mfma_f32_32x32x16_bf16 v[144:159], v[212:215], v[104:107], v[144:159]
	ds_read_b64_tr_b16 v[200:201], v182 offset:0
	ds_read_b64_tr_b16 v[202:203], v182 offset:2048
	v_cvt_pk_bf16_f32 v195, v86, v87
	v_add_f32_e32 v222, v222, v86
	v_add_f32_e32 v254, v254, v87
	s_waitcnt lgkmcnt(5)
	v_mfma_f32_32x32x16_bf16 v[128:143], v[230:233], v[100:103], v[128:143]
	ds_read_b64_tr_b16 v[204:205], v182 offset:512
	ds_read_b64_tr_b16 v[206:207], v182 offset:2560
	v_cvt_pk_bf16_f32 v196, v88, v89
	v_add_f32_e32 v169, v169, v88
	v_add_f32_e32 v219, v219, v89
	v_permlane32_swap_b32_e32 v192, v194
	s_waitcnt lgkmcnt(6)
	v_mfma_f32_32x32x16_bf16 v[144:159], v[234:237], v[100:103], v[144:159]
	ds_read_b64_tr_b16 v[208:209], v182 offset:1024
	ds_read_b64_tr_b16 v[210:211], v182 offset:3072
	v_cvt_pk_bf16_f32 v197, v90, v91
	v_add_f32_e32 v222, v222, v90
	v_add_f32_e32 v254, v254, v91
	v_permlane32_swap_b32_e32 v193, v195
	s_waitcnt lgkmcnt(7)
	v_mfma_f32_32x32x16_bf16 v[128:143], v[238:241], v[96:99], v[128:143]
	ds_read_b64_tr_b16 v[212:213], v182 offset:1536
	ds_read_b64_tr_b16 v[214:215], v182 offset:3584
	v_cvt_pk_bf16_f32 v198, v92, v93
	v_add_f32_e32 v169, v169, v92
	v_add_f32_e32 v219, v219, v93
	s_waitcnt lgkmcnt(8)
	v_mfma_f32_32x32x16_bf16 v[144:159], v[242:245], v[96:99], v[144:159]
	ds_read_b64_tr_b16 v[230:231], v182 offset:4096
	ds_read_b64_tr_b16 v[232:233], v182 offset:6144
	v_cvt_pk_bf16_f32 v199, v94, v95
	v_add_f32_e32 v222, v222, v94
	v_add_f32_e32 v254, v254, v95
	v_permlane32_swap_b32_e32 v196, v198
	v_permlane32_swap_b32_e32 v197, v199
	s_waitcnt lgkmcnt(8)
	v_mfma_f32_32x32x16_bf16 v[0:15], v[184:187], v[200:203], v[0:15]
	ds_read_b64_tr_b16 v[234:235], v182 offset:4608
	ds_read_b64_tr_b16 v[236:237], v182 offset:6656
	v_exp_f32_e32 v128, v128
	v_exp_f32_e32 v129, v129
	s_waitcnt lgkmcnt(8)
	v_mfma_f32_32x32x16_bf16 v[48:63], v[184:187], v[204:207], v[48:63]
	ds_read_b64_tr_b16 v[238:239], v182 offset:5120
	ds_read_b64_tr_b16 v[240:241], v182 offset:7168
	v_exp_f32_e32 v130, v130
	v_exp_f32_e32 v131, v131
	s_waitcnt vmcnt(3)
	ds_write_b128 v181, v[246:249] offset:49152
	s_waitcnt lgkmcnt(9)
	v_mfma_f32_32x32x16_bf16 v[32:47], v[184:187], v[208:211], v[32:47]
	ds_read_b64_tr_b16 v[242:243], v182 offset:5632
	ds_read_b64_tr_b16 v[244:245], v182 offset:7680
	v_exp_f32_e32 v132, v132
	v_exp_f32_e32 v133, v133
	s_waitcnt lgkmcnt(9)
	v_mfma_f32_32x32x16_bf16 v[16:31], v[184:187], v[212:215], v[16:31]
	ds_read_b64_tr_b16 v[200:201], v182 offset:8192
	ds_read_b64_tr_b16 v[202:203], v182 offset:10240
	v_exp_f32_e32 v134, v134
	v_exp_f32_e32 v135, v135
	s_waitcnt vmcnt(2)
; __device__ __forceinline__ void finishSM(f32x16& p0, f32x16& p1, float alpha, float& l_reg, bf16x8& pa0, bf16x8& pa1, bf16x8& pa2, bf16x8& pa3) {
; #pragma unroll
;   for (int r = 0; r < 16; ++r) p1[r] = __builtin_amdgcn_exp2f(p1[r]);
;   float ps = 0;
; #pragma unroll
;   for (int r = 0; r < 16; ++r) ps += p0[r];
; #pragma unroll
;   for (int r = 0; r < 16; ++r) ps += p1[r];
;   { auto rr = __builtin_amdgcn_permlane32_swap(__float_as_uint(ps), __float_as_uint(ps), false, false);
;     ps = __uint_as_float(rr[0]) + __uint_as_float(rr[1]); }
;   l_reg = l_reg * alpha + ps;
;     ...
;   PK4(p0, 0, pa0); PK4(p0, 8, pa1); PK4(p1, 0, pa2); PK4(p1, 8, pa3);
;     ...
; }
; __device__ __forceinline__ void qkt(f32x16& p0, f32x16& p1, const bf16* Ks, const bf16x8* qr, int r32, int hi) {
;   p0 = f32x16{}; p1 = f32x16{};
; #pragma unroll
;   for (int d0 = 0; d0 < 8; ++d0) { int cb = (d0 * 16 + hi * 8) * 2;
;     bf16x8 b0 = *reinterpret_cast<const bf16x8*>((const char*)Ks + KSWZ(r32, cb));
;     bf16x8 b1 = *reinterpret_cast<const bf16x8*>((const char*)Ks + KSWZ(32 + r32, cb));
;     p0 = __builtin_amdgcn_mfma_f32_32x32x16_bf16(b0, qr[d0], p0, 0, 0, 0);
;     p1 = __builtin_amdgcn_mfma_f32_32x32x16_bf16(b1, qr[d0], p1, 0, 0, 0); }
; }
; __device__ __forceinline__ int v_st(int k, int c) { const int kk = (k & ~0xC) | ((k & 4) << 1) | ((k & 8) >> 1); return ((kk >> 3) * 4 + (c >> 5)) * 512 + ((kk & 7) * 32 + (c & 31)) * 2; }
; __device__ __forceinline__ int v_rd_base(int lane) { return ((lane & 3) << 3) | (((lane >> 2) & 3) << 6) | (((lane >> 4) & 1) << 5) | (((lane >> 5) & 1) << 8); }
; template <int OFF> __device__ __forceinline__ s16x4 tr_read(int vb) {
;   s16x4 r; asm volatile("ds_read_b64_tr_b16 %0, %1 offset:%2" : "=&v"(r) : "v"(vb), "i"(OFF) : "memory"); return r;
; }
; template <int D0> __device__ __forceinline__ void pv_one(f32x16& od, int vb, bf16x8 pa0, bf16x8 pa1, bf16x8 pa2, bf16x8 pa3) {
;   const s16x4 l0 = tr_read<v_rd_off(D0, 0, 0)>(vb), h0 = tr_read<v_rd_off(D0, 0, 1)>(vb), l1 = tr_read<v_rd_off(D0, 1, 0)>(vb), h1 = tr_read<v_rd_off(D0, 1, 1)>(vb);
;   const s16x4 l2 = tr_read<v_rd_off(D0, 2, 0)>(vb), h2 = tr_read<v_rd_off(D0, 2, 1)>(vb), l3 = tr_read<v_rd_off(D0, 3, 0)>(vb), h3 = tr_read<v_rd_off(D0, 3, 1)>(vb);
;   asm volatile("s_waitcnt lgkmcnt(0)" ::: "memory"); SBAR();
;     ...
;   od = __builtin_amdgcn_mfma_f32_32x32x16_bf16(pa0, PK(l0, h0), od, 0, 0, 0);
	ds_write_b128 v181, v[250:253] offset:57344
	s_waitcnt lgkmcnt(10)
	v_mfma_f32_32x32x16_bf16 v[0:15], v[188:191], v[230:233], v[0:15]
	ds_read_b64_tr_b16 v[204:205], v182 offset:8704
	ds_read_b64_tr_b16 v[206:207], v182 offset:10752
	v_exp_f32_e32 v136, v136
	v_exp_f32_e32 v137, v137
	s_waitcnt lgkmcnt(10)
	v_mfma_f32_32x32x16_bf16 v[48:63], v[188:191], v[234:237], v[48:63]
	ds_read_b64_tr_b16 v[208:209], v182 offset:9216
	ds_read_b64_tr_b16 v[210:211], v182 offset:11264
	v_exp_f32_e32 v138, v138
	v_exp_f32_e32 v139, v139
	s_waitcnt vmcnt(1)
	ds_write_b128 v180, v[164:167] offset:32768
	s_waitcnt lgkmcnt(11)
	v_mfma_f32_32x32x16_bf16 v[32:47], v[188:191], v[238:241], v[32:47]
	ds_read_b64_tr_b16 v[212:213], v182 offset:9728
	ds_read_b64_tr_b16 v[214:215], v182 offset:11776
	v_exp_f32_e32 v140, v140
	v_exp_f32_e32 v141, v141
	s_waitcnt lgkmcnt(10)
	v_mfma_f32_32x32x16_bf16 v[16:31], v[188:191], v[242:245], v[16:31]
	ds_read_b64_tr_b16 v[230:231], v182 offset:12288
	ds_read_b64_tr_b16 v[232:233], v182 offset:14336
	v_exp_f32_e32 v142, v142
	v_exp_f32_e32 v143, v143
	s_waitcnt vmcnt(0)
	ds_write_b128 v180, v[160:163] offset:40960
	s_waitcnt lgkmcnt(11)
	v_mfma_f32_32x32x16_bf16 v[0:15], v[192:195], v[200:203], v[0:15]
	ds_read_b64_tr_b16 v[234:235], v182 offset:12800
	ds_read_b64_tr_b16 v[236:237], v182 offset:14848
	ds_read_b128 v[200:203], v172 offset:32768
	v_exp_f32_e32 v144, v144
	v_exp_f32_e32 v145, v145
	s_waitcnt lgkmcnt(11)
	v_mfma_f32_32x32x16_bf16 v[48:63], v[192:195], v[204:207], v[48:63]
	ds_read_b64_tr_b16 v[238:239], v182 offset:13312
	ds_read_b64_tr_b16 v[240:241], v182 offset:15360
	ds_read_b128 v[204:207], v172 offset:40960
	v_exp_f32_e32 v146, v146
	v_exp_f32_e32 v147, v147
	s_waitcnt lgkmcnt(12)
	v_mfma_f32_32x32x16_bf16 v[32:47], v[192:195], v[208:211], v[32:47]
	ds_read_b64_tr_b16 v[242:243], v182 offset:13824
	ds_read_b64_tr_b16 v[244:245], v182 offset:15872
	ds_read_b128 v[208:211], v173 offset:32768
	v_exp_f32_e32 v148, v148
	v_exp_f32_e32 v149, v149
	s_waitcnt lgkmcnt(12)
	v_mfma_f32_32x32x16_bf16 v[16:31], v[192:195], v[212:215], v[16:31]
	ds_read_b128 v[212:215], v173 offset:40960
	v_exp_f32_e32 v150, v150
	v_exp_f32_e32 v151, v151
	s_waitcnt lgkmcnt(11)
	v_mfma_f32_32x32x16_bf16 v[0:15], v[196:199], v[230:233], v[0:15]
	ds_read_b128 v[230:233], v174 offset:32768
	v_exp_f32_e32 v152, v152
	v_exp_f32_e32 v153, v153
	s_waitcnt lgkmcnt(9)
	v_mfma_f32_32x32x16_bf16 v[48:63], v[196:199], v[234:237], v[48:63]
	ds_read_b128 v[234:237], v174 offset:40960
	v_exp_f32_e32 v154, v154
	v_exp_f32_e32 v155, v155
	s_waitcnt lgkmcnt(7)
	v_mfma_f32_32x32x16_bf16 v[32:47], v[196:199], v[238:241], v[32:47]
	ds_read_b128 v[238:241], v175 offset:32768
	v_exp_f32_e32 v156, v156
	v_exp_f32_e32 v157, v157
	s_waitcnt lgkmcnt(5)
	v_mfma_f32_32x32x16_bf16 v[16:31], v[196:199], v[242:245], v[16:31]
	ds_read_b128 v[242:245], v175 offset:40960
	v_exp_f32_e32 v158, v158
	v_exp_f32_e32 v159, v159
	s_barrier
	v_mfma_f32_32x32x16_bf16 v[64:79], v[200:203], v[124:127], 0
	ds_read_b128 v[200:203], v176 offset:32768
	v_cvt_pk_bf16_f32 v184, v128, v129
	v_add_f32_e32 v169, v169, v128
	v_add_f32_e32 v219, v219, v129
	global_load_dwordx4 v[246:249], v183, s[98:99]
	v_mfma_f32_32x32x16_bf16 v[80:95], v[204:207], v[124:127], 0
	ds_read_b128 v[204:207], v176 offset:40960
	v_cvt_pk_bf16_f32 v185, v130, v131
	v_add_f32_e32 v222, v222, v130
	v_add_f32_e32 v254, v254, v131
	s_waitcnt lgkmcnt(7)
	v_mfma_f32_32x32x16_bf16 v[64:79], v[208:211], v[120:123], v[64:79]
	ds_read_b128 v[208:211], v177 offset:32768
	v_cvt_pk_bf16_f32 v186, v132, v133
	v_add_f32_e32 v169, v169, v132
	v_add_f32_e32 v219, v219, v133
	global_load_dwordx4 v[250:253], v183, s[100:101]
	s_add_u32 s98, s98, 0x150000
	s_addc_u32 s99, s99, 0
	s_add_u32 s100, s100, 0x150000
	s_addc_u32 s101, s101, 0
	s_waitcnt lgkmcnt(7)
	v_mfma_f32_32x32x16_bf16 v[80:95], v[212:215], v[120:123], v[80:95]
	ds_read_b128 v[212:215], v177 offset:40960
	v_cvt_pk_bf16_f32 v187, v134, v135
	v_add_f32_e32 v222, v222, v134
	v_add_f32_e32 v254, v254, v135
	s_waitcnt lgkmcnt(7)
	v_mfma_f32_32x32x16_bf16 v[64:79], v[230:233], v[116:119], v[64:79]
	ds_read_b128 v[230:233], v178 offset:32768
	v_cvt_pk_bf16_f32 v188, v136, v137
	v_add_f32_e32 v169, v169, v136
	v_add_f32_e32 v219, v219, v137
	v_permlane32_swap_b32_e32 v184, v186
	global_load_dwordx4 v[164:167], v183, s[0:1] offset:512
	s_waitcnt lgkmcnt(7)
	v_mfma_f32_32x32x16_bf16 v[80:95], v[234:237], v[116:119], v[80:95]
	ds_read_b128 v[234:237], v178 offset:40960
	v_cvt_pk_bf16_f32 v189, v138, v139
	v_add_f32_e32 v222, v222, v138
	v_add_f32_e32 v254, v254, v139
	v_permlane32_swap_b32_e32 v185, v187
	s_waitcnt lgkmcnt(7)
	v_mfma_f32_32x32x16_bf16 v[64:79], v[238:241], v[112:115], v[64:79]
	ds_read_b128 v[238:241], v179 offset:32768
	v_cvt_pk_bf16_f32 v190, v140, v141
	v_add_f32_e32 v169, v169, v140
	v_add_f32_e32 v219, v219, v141
	global_load_dwordx4 v[160:163], v183, s[4:5] offset:512
	s_add_u32 s0, s0, 0x150000
	s_addc_u32 s1, s1, 0
	s_add_u32 s4, s4, 0x150000
	s_addc_u32 s5, s5, 0
	s_waitcnt lgkmcnt(7)
	v_mfma_f32_32x32x16_bf16 v[80:95], v[242:245], v[112:115], v[80:95]
	ds_read_b128 v[242:245], v179 offset:40960
	v_cvt_pk_bf16_f32 v191, v142, v143
	v_add_f32_e32 v222, v222, v142
	v_add_f32_e32 v254, v254, v143
	s_waitcnt lgkmcnt(7)
	v_mfma_f32_32x32x16_bf16 v[64:79], v[200:203], v[108:111], v[64:79]
	v_cvt_pk_bf16_f32 v192, v144, v145
	v_add_f32_e32 v169, v169, v144
	v_add_f32_e32 v219, v219, v145
	v_permlane32_swap_b32_e32 v188, v190
	s_waitcnt lgkmcnt(6)
; __device__ __forceinline__ void finishSM(f32x16& p0, f32x16& p1, float alpha, float& l_reg, bf16x8& pa0, bf16x8& pa1, bf16x8& pa2, bf16x8& pa3) {
; #pragma unroll
;   for (int r = 0; r < 16; ++r) p1[r] = __builtin_amdgcn_exp2f(p1[r]);
;   float ps = 0;
; #pragma unroll
;   for (int r = 0; r < 16; ++r) ps += p0[r];
; #pragma unroll
;   for (int r = 0; r < 16; ++r) ps += p1[r];
;   { auto rr = __builtin_amdgcn_permlane32_swap(__float_as_uint(ps), __float_as_uint(ps), false, false);
;     ps = __uint_as_float(rr[0]) + __uint_as_float(rr[1]); }
;   l_reg = l_reg * alpha + ps;
;     ...
;   PK4(p0, 0, pa0); PK4(p0, 8, pa1); PK4(p1, 0, pa2); PK4(p1, 8, pa3);
;     ...
; }
; __device__ __forceinline__ void qkt(f32x16& p0, f32x16& p1, const bf16* Ks, const bf16x8* qr, int r32, int hi) {
;   p0 = f32x16{}; p1 = f32x16{};
; #pragma unroll
;   for (int d0 = 0; d0 < 8; ++d0) { int cb = (d0 * 16 + hi * 8) * 2;
;     bf16x8 b0 = *reinterpret_cast<const bf16x8*>((const char*)Ks + KSWZ(r32, cb));
;     bf16x8 b1 = *reinterpret_cast<const bf16x8*>((const char*)Ks + KSWZ(32 + r32, cb));
;     p0 = __builtin_amdgcn_mfma_f32_32x32x16_bf16(b0, qr[d0], p0, 0, 0, 0);
;     p1 = __builtin_amdgcn_mfma_f32_32x32x16_bf16(b1, qr[d0], p1, 0, 0, 0); }
; }
; __device__ __forceinline__ int v_st(int k, int c) { const int kk = (k & ~0xC) | ((k & 4) << 1) | ((k & 8) >> 1); return ((kk >> 3) * 4 + (c >> 5)) * 512 + ((kk & 7) * 32 + (c & 31)) * 2; }
; __device__ __forceinline__ int v_rd_base(int lane) { return ((lane & 3) << 3) | (((lane >> 2) & 3) << 6) | (((lane >> 4) & 1) << 5) | (((lane >> 5) & 1) << 8); }
; template <int OFF> __device__ __forceinline__ s16x4 tr_read(int vb) {
;   s16x4 r; asm volatile("ds_read_b64_tr_b16 %0, %1 offset:%2" : "=&v"(r) : "v"(vb), "i"(OFF) : "memory"); return r;
; }
; template <int D0> __device__ __forceinline__ void pv_one(f32x16& od, int vb, bf16x8 pa0, bf16x8 pa1, bf16x8 pa2, bf16x8 pa3) {
;   const s16x4 l0 = tr_read<v_rd_off(D0, 0, 0)>(vb), h0 = tr_read<v_rd_off(D0, 0, 1)>(vb), l1 = tr_read<v_rd_off(D0, 1, 0)>(vb), h1 = tr_read<v_rd_off(D0, 1, 1)>(vb);
;   const s16x4 l2 = tr_read<v_rd_off(D0, 2, 0)>(vb), h2 = tr_read<v_rd_off(D0, 2, 1)>(vb), l3 = tr_read<v_rd_off(D0, 3, 0)>(vb), h3 = tr_read<v_rd_off(D0, 3, 1)>(vb);
;   asm volatile("s_waitcnt lgkmcnt(0)" ::: "memory"); SBAR();
;     ...
;   od = __builtin_amdgcn_mfma_f32_32x32x16_bf16(pa0, PK(l0, h0), od, 0, 0, 0);
	v_mfma_f32_32x32x16_bf16 v[80:95], v[204:207], v[108:111], v[80:95]
	v_cvt_pk_bf16_f32 v193, v146, v147
	v_add_f32_e32 v222, v222, v146
	v_add_f32_e32 v254, v254, v147
	v_permlane32_swap_b32_e32 v189, v191
	s_waitcnt lgkmcnt(5)
	v_mfma_f32_32x32x16_bf16 v[64:79], v[208:211], v[104:107], v[64:79]
	v_cvt_pk_bf16_f32 v194, v148, v149
	v_add_f32_e32 v169, v169, v148
	v_add_f32_e32 v219, v219, v149
	s_waitcnt lgkmcnt(4)
	v_mfma_f32_32x32x16_bf16 v[80:95], v[212:215], v[104:107], v[80:95]
	ds_read_b64_tr_b16 v[200:201], v182 offset:16384
	ds_read_b64_tr_b16 v[202:203], v182 offset:18432
	v_cvt_pk_bf16_f32 v195, v150, v151
	v_add_f32_e32 v222, v222, v150
	v_add_f32_e32 v254, v254, v151
	s_waitcnt lgkmcnt(5)
	v_mfma_f32_32x32x16_bf16 v[64:79], v[230:233], v[100:103], v[64:79]
	ds_read_b64_tr_b16 v[204:205], v182 offset:16896
	ds_read_b64_tr_b16 v[206:207], v182 offset:18944
	v_cvt_pk_bf16_f32 v196, v152, v153
	v_add_f32_e32 v169, v169, v152
	v_add_f32_e32 v219, v219, v153
	v_permlane32_swap_b32_e32 v192, v194
	s_waitcnt lgkmcnt(6)
	v_mfma_f32_32x32x16_bf16 v[80:95], v[234:237], v[100:103], v[80:95]
	ds_read_b64_tr_b16 v[208:209], v182 offset:17408
	ds_read_b64_tr_b16 v[210:211], v182 offset:19456
	v_cvt_pk_bf16_f32 v197, v154, v155
	v_add_f32_e32 v222, v222, v154
	v_add_f32_e32 v254, v254, v155
	v_permlane32_swap_b32_e32 v193, v195
	s_waitcnt lgkmcnt(7)
	v_mfma_f32_32x32x16_bf16 v[64:79], v[238:241], v[96:99], v[64:79]
	ds_read_b64_tr_b16 v[212:213], v182 offset:17920
	ds_read_b64_tr_b16 v[214:215], v182 offset:19968
	v_cvt_pk_bf16_f32 v198, v156, v157
	v_add_f32_e32 v169, v169, v156
	v_add_f32_e32 v219, v219, v157
	s_waitcnt lgkmcnt(8)
	v_mfma_f32_32x32x16_bf16 v[80:95], v[242:245], v[96:99], v[80:95]
	ds_read_b64_tr_b16 v[230:231], v182 offset:20480
	ds_read_b64_tr_b16 v[232:233], v182 offset:22528
	v_cvt_pk_bf16_f32 v199, v158, v159
	v_add_f32_e32 v222, v222, v158
	v_add_f32_e32 v254, v254, v159
	v_permlane32_swap_b32_e32 v196, v198
	v_permlane32_swap_b32_e32 v197, v199
	s_waitcnt lgkmcnt(8)
	v_mfma_f32_32x32x16_bf16 v[0:15], v[184:187], v[200:203], v[0:15]
	ds_read_b64_tr_b16 v[234:235], v182 offset:20992
	ds_read_b64_tr_b16 v[236:237], v182 offset:23040
	v_exp_f32_e32 v64, v64
	v_exp_f32_e32 v65, v65
	s_waitcnt lgkmcnt(8)
	v_mfma_f32_32x32x16_bf16 v[48:63], v[184:187], v[204:207], v[48:63]
	ds_read_b64_tr_b16 v[238:239], v182 offset:21504
	ds_read_b64_tr_b16 v[240:241], v182 offset:23552
	v_exp_f32_e32 v66, v66
	v_exp_f32_e32 v67, v67
	s_waitcnt vmcnt(3)
	ds_write_b128 v181, v[246:249] offset:0
	s_waitcnt lgkmcnt(9)
	v_mfma_f32_32x32x16_bf16 v[32:47], v[184:187], v[208:211], v[32:47]
	ds_read_b64_tr_b16 v[242:243], v182 offset:22016
	ds_read_b64_tr_b16 v[244:245], v182 offset:24064
	v_exp_f32_e32 v68, v68
	v_exp_f32_e32 v69, v69
	s_waitcnt lgkmcnt(9)
	v_mfma_f32_32x32x16_bf16 v[16:31], v[184:187], v[212:215], v[16:31]
	ds_read_b64_tr_b16 v[200:201], v182 offset:24576
	ds_read_b64_tr_b16 v[202:203], v182 offset:26624
	v_exp_f32_e32 v70, v70
	v_exp_f32_e32 v71, v71
	s_waitcnt vmcnt(2)
	ds_write_b128 v181, v[250:253] offset:8192
	s_waitcnt lgkmcnt(10)
	v_mfma_f32_32x32x16_bf16 v[0:15], v[188:191], v[230:233], v[0:15]
	ds_read_b64_tr_b16 v[204:205], v182 offset:25088
	ds_read_b64_tr_b16 v[206:207], v182 offset:27136
	v_exp_f32_e32 v72, v72
	v_exp_f32_e32 v73, v73
	s_waitcnt lgkmcnt(10)
	v_mfma_f32_32x32x16_bf16 v[48:63], v[188:191], v[234:237], v[48:63]
	ds_read_b64_tr_b16 v[208:209], v182 offset:25600
	ds_read_b64_tr_b16 v[210:211], v182 offset:27648
	v_exp_f32_e32 v74, v74
	v_exp_f32_e32 v75, v75
	s_waitcnt vmcnt(1)
	ds_write_b128 v180, v[164:167] offset:49152
	s_waitcnt lgkmcnt(11)
	v_mfma_f32_32x32x16_bf16 v[32:47], v[188:191], v[238:241], v[32:47]
	ds_read_b64_tr_b16 v[212:213], v182 offset:26112
	ds_read_b64_tr_b16 v[214:215], v182 offset:28160
	v_exp_f32_e32 v76, v76
	v_exp_f32_e32 v77, v77
	s_waitcnt lgkmcnt(10)
	v_mfma_f32_32x32x16_bf16 v[16:31], v[188:191], v[242:245], v[16:31]
	ds_read_b64_tr_b16 v[230:231], v182 offset:28672
	ds_read_b64_tr_b16 v[232:233], v182 offset:30720
	v_exp_f32_e32 v78, v78
	v_exp_f32_e32 v79, v79
	s_waitcnt vmcnt(0)
	ds_write_b128 v180, v[160:163] offset:57344
	s_waitcnt lgkmcnt(11)
	v_mfma_f32_32x32x16_bf16 v[0:15], v[192:195], v[200:203], v[0:15]
	ds_read_b64_tr_b16 v[234:235], v182 offset:29184
	ds_read_b64_tr_b16 v[236:237], v182 offset:31232
	ds_read_b128 v[200:203], v172 offset:49152
	v_exp_f32_e32 v80, v80
	v_exp_f32_e32 v81, v81
	s_waitcnt lgkmcnt(11)
	v_mfma_f32_32x32x16_bf16 v[48:63], v[192:195], v[204:207], v[48:63]
	ds_read_b64_tr_b16 v[238:239], v182 offset:29696
	ds_read_b64_tr_b16 v[240:241], v182 offset:31744
	ds_read_b128 v[204:207], v172 offset:57344
	v_exp_f32_e32 v82, v82
	v_exp_f32_e32 v83, v83
	s_waitcnt lgkmcnt(12)
	v_mfma_f32_32x32x16_bf16 v[32:47], v[192:195], v[208:211], v[32:47]
	ds_read_b64_tr_b16 v[242:243], v182 offset:30208
	ds_read_b64_tr_b16 v[244:245], v182 offset:32256
	ds_read_b128 v[208:211], v173 offset:49152
	v_exp_f32_e32 v84, v84
	v_exp_f32_e32 v85, v85
	s_waitcnt lgkmcnt(12)
	v_mfma_f32_32x32x16_bf16 v[16:31], v[192:195], v[212:215], v[16:31]
	ds_read_b128 v[212:215], v173 offset:57344
	v_exp_f32_e32 v86, v86
	v_exp_f32_e32 v87, v87
	s_waitcnt lgkmcnt(11)
	v_mfma_f32_32x32x16_bf16 v[0:15], v[196:199], v[230:233], v[0:15]
	ds_read_b128 v[230:233], v174 offset:49152
	v_exp_f32_e32 v88, v88
	v_exp_f32_e32 v89, v89
	s_waitcnt lgkmcnt(9)
	v_mfma_f32_32x32x16_bf16 v[48:63], v[196:199], v[234:237], v[48:63]
	ds_read_b128 v[234:237], v174 offset:57344
	v_exp_f32_e32 v90, v90
	v_exp_f32_e32 v91, v91
	s_waitcnt lgkmcnt(7)
	v_mfma_f32_32x32x16_bf16 v[32:47], v[196:199], v[238:241], v[32:47]
	ds_read_b128 v[238:241], v175 offset:49152
	v_exp_f32_e32 v92, v92
	v_exp_f32_e32 v93, v93
	s_waitcnt lgkmcnt(5)
	v_mfma_f32_32x32x16_bf16 v[16:31], v[196:199], v[242:245], v[16:31]
	ds_read_b128 v[242:245], v175 offset:57344
	v_exp_f32_e32 v94, v94
	v_exp_f32_e32 v95, v95
	s_barrier
; __device__ __forceinline__ void finishSM(f32x16& p0, f32x16& p1, float alpha, float& l_reg, bf16x8& pa0, bf16x8& pa1, bf16x8& pa2, bf16x8& pa3) {
; #pragma unroll
;   for (int r = 0; r < 16; ++r) p1[r] = __builtin_amdgcn_exp2f(p1[r]);
;   float ps = 0;
; #pragma unroll
;   for (int r = 0; r < 16; ++r) ps += p0[r];
; #pragma unroll
;   for (int r = 0; r < 16; ++r) ps += p1[r];
;   { auto rr = __builtin_amdgcn_permlane32_swap(__float_as_uint(ps), __float_as_uint(ps), false, false);
;     ps = __uint_as_float(rr[0]) + __uint_as_float(rr[1]); }
;   l_reg = l_reg * alpha + ps;
;     ...
;   PK4(p0, 0, pa0); PK4(p0, 8, pa1); PK4(p1, 0, pa2); PK4(p1, 8, pa3);
;     ...
; }
; __device__ __forceinline__ void qkt(f32x16& p0, f32x16& p1, const bf16* Ks, const bf16x8* qr, int r32, int hi) {
;   p0 = f32x16{}; p1 = f32x16{};
; #pragma unroll
;   for (int d0 = 0; d0 < 8; ++d0) { int cb = (d0 * 16 + hi * 8) * 2;
;     bf16x8 b0 = *reinterpret_cast<const bf16x8*>((const char*)Ks + KSWZ(r32, cb));
;     bf16x8 b1 = *reinterpret_cast<const bf16x8*>((const char*)Ks + KSWZ(32 + r32, cb));
;     p0 = __builtin_amdgcn_mfma_f32_32x32x16_bf16(b0, qr[d0], p0, 0, 0, 0);
;     p1 = __builtin_amdgcn_mfma_f32_32x32x16_bf16(b1, qr[d0], p1, 0, 0, 0); }
; }
; __device__ __forceinline__ int v_st(int k, int c) { const int kk = (k & ~0xC) | ((k & 4) << 1) | ((k & 8) >> 1); return ((kk >> 3) * 4 + (c >> 5)) * 512 + ((kk & 7) * 32 + (c & 31)) * 2; }
; __device__ __forceinline__ int v_rd_base(int lane) { return ((lane & 3) << 3) | (((lane >> 2) & 3) << 6) | (((lane >> 4) & 1) << 5) | (((lane >> 5) & 1) << 8); }
; template <int OFF> __device__ __forceinline__ s16x4 tr_read(int vb) {
;   s16x4 r; asm volatile("ds_read_b64_tr_b16 %0, %1 offset:%2" : "=&v"(r) : "v"(vb), "i"(OFF) : "memory"); return r;
; }
; template <int D0> __device__ __forceinline__ void pv_one(f32x16& od, int vb, bf16x8 pa0, bf16x8 pa1, bf16x8 pa2, bf16x8 pa3) {
;   const s16x4 l0 = tr_read<v_rd_off(D0, 0, 0)>(vb), h0 = tr_read<v_rd_off(D0, 0, 1)>(vb), l1 = tr_read<v_rd_off(D0, 1, 0)>(vb), h1 = tr_read<v_rd_off(D0, 1, 1)>(vb);
;   const s16x4 l2 = tr_read<v_rd_off(D0, 2, 0)>(vb), h2 = tr_read<v_rd_off(D0, 2, 1)>(vb), l3 = tr_read<v_rd_off(D0, 3, 0)>(vb), h3 = tr_read<v_rd_off(D0, 3, 1)>(vb);
;   asm volatile("s_waitcnt lgkmcnt(0)" ::: "memory"); SBAR();
;     ...
;   od = __builtin_amdgcn_mfma_f32_32x32x16_bf16(pa0, PK(l0, h0), od, 0, 0, 0);
	v_mfma_f32_32x32x16_bf16 v[128:143], v[200:203], v[124:127], 0
	ds_read_b128 v[200:203], v176 offset:49152
	v_cvt_pk_bf16_f32 v184, v64, v65
	v_add_f32_e32 v169, v169, v64
	v_add_f32_e32 v219, v219, v65
	global_load_dwordx4 v[246:249], v183, s[98:99]
	v_mfma_f32_32x32x16_bf16 v[144:159], v[204:207], v[124:127], 0
	ds_read_b128 v[204:207], v176 offset:57344
	v_cvt_pk_bf16_f32 v185, v66, v67
	v_add_f32_e32 v222, v222, v66
	v_add_f32_e32 v254, v254, v67
	s_waitcnt lgkmcnt(7)
	v_mfma_f32_32x32x16_bf16 v[128:143], v[208:211], v[120:123], v[128:143]
	ds_read_b128 v[208:211], v177 offset:49152
	v_cvt_pk_bf16_f32 v186, v68, v69
	v_add_f32_e32 v169, v169, v68
	v_add_f32_e32 v219, v219, v69
	global_load_dwordx4 v[250:253], v183, s[100:101]
	s_add_u32 s98, s98, 0x150000
	s_addc_u32 s99, s99, 0
	s_add_u32 s100, s100, 0x150000
	s_addc_u32 s101, s101, 0
	s_waitcnt lgkmcnt(7)
	v_mfma_f32_32x32x16_bf16 v[144:159], v[212:215], v[120:123], v[144:159]
	ds_read_b128 v[212:215], v177 offset:57344
	v_cvt_pk_bf16_f32 v187, v70, v71
	v_add_f32_e32 v222, v222, v70
	v_add_f32_e32 v254, v254, v71
	s_waitcnt lgkmcnt(7)
	v_mfma_f32_32x32x16_bf16 v[128:143], v[230:233], v[116:119], v[128:143]
	ds_read_b128 v[230:233], v178 offset:49152
	v_cvt_pk_bf16_f32 v188, v72, v73
	v_add_f32_e32 v169, v169, v72
	v_add_f32_e32 v219, v219, v73
	v_permlane32_swap_b32_e32 v184, v186
	global_load_dwordx4 v[164:167], v183, s[0:1] offset:512
	s_waitcnt lgkmcnt(7)
	v_mfma_f32_32x32x16_bf16 v[144:159], v[234:237], v[116:119], v[144:159]
	ds_read_b128 v[234:237], v178 offset:57344
	v_cvt_pk_bf16_f32 v189, v74, v75
	v_add_f32_e32 v222, v222, v74
	v_add_f32_e32 v254, v254, v75
	v_permlane32_swap_b32_e32 v185, v187
	s_waitcnt lgkmcnt(7)
	v_mfma_f32_32x32x16_bf16 v[128:143], v[238:241], v[112:115], v[128:143]
	ds_read_b128 v[238:241], v179 offset:49152
	v_cvt_pk_bf16_f32 v190, v76, v77
	v_add_f32_e32 v169, v169, v76
	v_add_f32_e32 v219, v219, v77
	global_load_dwordx4 v[160:163], v183, s[4:5] offset:512
	s_add_u32 s0, s0, 0x150000
	s_addc_u32 s1, s1, 0
	s_add_u32 s4, s4, 0x150000
	s_addc_u32 s5, s5, 0
	s_waitcnt lgkmcnt(7)
	v_mfma_f32_32x32x16_bf16 v[144:159], v[242:245], v[112:115], v[144:159]
	ds_read_b128 v[242:245], v179 offset:57344
	v_cvt_pk_bf16_f32 v191, v78, v79
	v_add_f32_e32 v222, v222, v78
	v_add_f32_e32 v254, v254, v79
	s_waitcnt lgkmcnt(7)
	v_mfma_f32_32x32x16_bf16 v[128:143], v[200:203], v[108:111], v[128:143]
	v_cvt_pk_bf16_f32 v192, v80, v81
	v_add_f32_e32 v169, v169, v80
	v_add_f32_e32 v219, v219, v81
	v_permlane32_swap_b32_e32 v188, v190
	s_waitcnt lgkmcnt(6)
	v_mfma_f32_32x32x16_bf16 v[144:159], v[204:207], v[108:111], v[144:159]
	v_cvt_pk_bf16_f32 v193, v82, v83
	v_add_f32_e32 v222, v222, v82
	v_add_f32_e32 v254, v254, v83
	v_permlane32_swap_b32_e32 v189, v191
	s_waitcnt lgkmcnt(5)
	v_mfma_f32_32x32x16_bf16 v[128:143], v[208:211], v[104:107], v[128:143]
	v_cvt_pk_bf16_f32 v194, v84, v85
	v_add_f32_e32 v169, v169, v84
	v_add_f32_e32 v219, v219, v85
	s_waitcnt lgkmcnt(4)
	v_mfma_f32_32x32x16_bf16 v[144:159], v[212:215], v[104:107], v[144:159]
	ds_read_b64_tr_b16 v[200:201], v182 offset:32768
	ds_read_b64_tr_b16 v[202:203], v182 offset:34816
	v_cvt_pk_bf16_f32 v195, v86, v87
	v_add_f32_e32 v222, v222, v86
	v_add_f32_e32 v254, v254, v87
	s_waitcnt lgkmcnt(5)
	v_mfma_f32_32x32x16_bf16 v[128:143], v[230:233], v[100:103], v[128:143]
	ds_read_b64_tr_b16 v[204:205], v182 offset:33280
	ds_read_b64_tr_b16 v[206:207], v182 offset:35328
	v_cvt_pk_bf16_f32 v196, v88, v89
	v_add_f32_e32 v169, v169, v88
	v_add_f32_e32 v219, v219, v89
	v_permlane32_swap_b32_e32 v192, v194
	s_waitcnt lgkmcnt(6)
	v_mfma_f32_32x32x16_bf16 v[144:159], v[234:237], v[100:103], v[144:159]
	ds_read_b64_tr_b16 v[208:209], v182 offset:33792
	ds_read_b64_tr_b16 v[210:211], v182 offset:35840
	v_cvt_pk_bf16_f32 v197, v90, v91
	v_add_f32_e32 v222, v222, v90
	v_add_f32_e32 v254, v254, v91
	v_permlane32_swap_b32_e32 v193, v195
	s_waitcnt lgkmcnt(7)
	v_mfma_f32_32x32x16_bf16 v[128:143], v[238:241], v[96:99], v[128:143]
	ds_read_b64_tr_b16 v[212:213], v182 offset:34304
	ds_read_b64_tr_b16 v[214:215], v182 offset:36352
	v_cvt_pk_bf16_f32 v198, v92, v93
	v_add_f32_e32 v169, v169, v92
	v_add_f32_e32 v219, v219, v93
	s_waitcnt lgkmcnt(8)
	v_mfma_f32_32x32x16_bf16 v[144:159], v[242:245], v[96:99], v[144:159]
	ds_read_b64_tr_b16 v[230:231], v182 offset:36864
	ds_read_b64_tr_b16 v[232:233], v182 offset:38912
	v_cvt_pk_bf16_f32 v199, v94, v95
	v_add_f32_e32 v222, v222, v94
	v_add_f32_e32 v254, v254, v95
	v_permlane32_swap_b32_e32 v196, v198
	v_permlane32_swap_b32_e32 v197, v199
	s_waitcnt lgkmcnt(8)
	v_mfma_f32_32x32x16_bf16 v[0:15], v[184:187], v[200:203], v[0:15]
	ds_read_b64_tr_b16 v[234:235], v182 offset:37376
	ds_read_b64_tr_b16 v[236:237], v182 offset:39424
	v_exp_f32_e32 v128, v128
	v_exp_f32_e32 v129, v129
	s_waitcnt lgkmcnt(8)
	v_mfma_f32_32x32x16_bf16 v[48:63], v[184:187], v[204:207], v[48:63]
	ds_read_b64_tr_b16 v[238:239], v182 offset:37888
	ds_read_b64_tr_b16 v[240:241], v182 offset:39936
	v_exp_f32_e32 v130, v130
	v_exp_f32_e32 v131, v131
	s_waitcnt vmcnt(3)
	ds_write_b128 v181, v[246:249] offset:16384
	s_waitcnt lgkmcnt(9)
	v_mfma_f32_32x32x16_bf16 v[32:47], v[184:187], v[208:211], v[32:47]
	ds_read_b64_tr_b16 v[242:243], v182 offset:38400
	ds_read_b64_tr_b16 v[244:245], v182 offset:40448
	v_exp_f32_e32 v132, v132
	v_exp_f32_e32 v133, v133
	s_waitcnt lgkmcnt(9)
	v_mfma_f32_32x32x16_bf16 v[16:31], v[184:187], v[212:215], v[16:31]
	ds_read_b64_tr_b16 v[200:201], v182 offset:40960
	ds_read_b64_tr_b16 v[202:203], v182 offset:43008
	v_exp_f32_e32 v134, v134
	v_exp_f32_e32 v135, v135
	s_waitcnt vmcnt(2)
; __device__ __forceinline__ void finishSM(f32x16& p0, f32x16& p1, float alpha, float& l_reg, bf16x8& pa0, bf16x8& pa1, bf16x8& pa2, bf16x8& pa3) {
; #pragma unroll
;   for (int r = 0; r < 16; ++r) p1[r] = __builtin_amdgcn_exp2f(p1[r]);
;   float ps = 0;
; #pragma unroll
;   for (int r = 0; r < 16; ++r) ps += p0[r];
; #pragma unroll
;   for (int r = 0; r < 16; ++r) ps += p1[r];
;   { auto rr = __builtin_amdgcn_permlane32_swap(__float_as_uint(ps), __float_as_uint(ps), false, false);
;     ps = __uint_as_float(rr[0]) + __uint_as_float(rr[1]); }
;   l_reg = l_reg * alpha + ps;
;     ...
;   PK4(p0, 0, pa0); PK4(p0, 8, pa1); PK4(p1, 0, pa2); PK4(p1, 8, pa3);
;     ...
; }
; __device__ __forceinline__ void qkt(f32x16& p0, f32x16& p1, const bf16* Ks, const bf16x8* qr, int r32, int hi) {
;   p0 = f32x16{}; p1 = f32x16{};
; #pragma unroll
;   for (int d0 = 0; d0 < 8; ++d0) { int cb = (d0 * 16 + hi * 8) * 2;
;     bf16x8 b0 = *reinterpret_cast<const bf16x8*>((const char*)Ks + KSWZ(r32, cb));
;     bf16x8 b1 = *reinterpret_cast<const bf16x8*>((const char*)Ks + KSWZ(32 + r32, cb));
;     p0 = __builtin_amdgcn_mfma_f32_32x32x16_bf16(b0, qr[d0], p0, 0, 0, 0);
;     p1 = __builtin_amdgcn_mfma_f32_32x32x16_bf16(b1, qr[d0], p1, 0, 0, 0); }
; }
; __device__ __forceinline__ int v_st(int k, int c) { const int kk = (k & ~0xC) | ((k & 4) << 1) | ((k & 8) >> 1); return ((kk >> 3) * 4 + (c >> 5)) * 512 + ((kk & 7) * 32 + (c & 31)) * 2; }
; __device__ __forceinline__ int v_rd_base(int lane) { return ((lane & 3) << 3) | (((lane >> 2) & 3) << 6) | (((lane >> 4) & 1) << 5) | (((lane >> 5) & 1) << 8); }
; template <int OFF> __device__ __forceinline__ s16x4 tr_read(int vb) {
;   s16x4 r; asm volatile("ds_read_b64_tr_b16 %0, %1 offset:%2" : "=&v"(r) : "v"(vb), "i"(OFF) : "memory"); return r;
; }
; template <int D0> __device__ __forceinline__ void pv_one(f32x16& od, int vb, bf16x8 pa0, bf16x8 pa1, bf16x8 pa2, bf16x8 pa3) {
;   const s16x4 l0 = tr_read<v_rd_off(D0, 0, 0)>(vb), h0 = tr_read<v_rd_off(D0, 0, 1)>(vb), l1 = tr_read<v_rd_off(D0, 1, 0)>(vb), h1 = tr_read<v_rd_off(D0, 1, 1)>(vb);
;   const s16x4 l2 = tr_read<v_rd_off(D0, 2, 0)>(vb), h2 = tr_read<v_rd_off(D0, 2, 1)>(vb), l3 = tr_read<v_rd_off(D0, 3, 0)>(vb), h3 = tr_read<v_rd_off(D0, 3, 1)>(vb);
;   asm volatile("s_waitcnt lgkmcnt(0)" ::: "memory"); SBAR();
;     ...
;   od = __builtin_amdgcn_mfma_f32_32x32x16_bf16(pa0, PK(l0, h0), od, 0, 0, 0);
	ds_write_b128 v181, v[250:253] offset:24576
	s_waitcnt lgkmcnt(10)
	v_mfma_f32_32x32x16_bf16 v[0:15], v[188:191], v[230:233], v[0:15]
	ds_read_b64_tr_b16 v[204:205], v182 offset:41472
	ds_read_b64_tr_b16 v[206:207], v182 offset:43520
	v_exp_f32_e32 v136, v136
	v_exp_f32_e32 v137, v137
	s_waitcnt lgkmcnt(10)
	v_mfma_f32_32x32x16_bf16 v[48:63], v[188:191], v[234:237], v[48:63]
	ds_read_b64_tr_b16 v[208:209], v182 offset:41984
	ds_read_b64_tr_b16 v[210:211], v182 offset:44032
	v_exp_f32_e32 v138, v138
	v_exp_f32_e32 v139, v139
	s_waitcnt vmcnt(1)
	ds_write_b128 v180, v[164:167] offset:0
	s_waitcnt lgkmcnt(11)
	v_mfma_f32_32x32x16_bf16 v[32:47], v[188:191], v[238:241], v[32:47]
	ds_read_b64_tr_b16 v[212:213], v182 offset:42496
	ds_read_b64_tr_b16 v[214:215], v182 offset:44544
	v_exp_f32_e32 v140, v140
	v_exp_f32_e32 v141, v141
	s_waitcnt lgkmcnt(10)
	v_mfma_f32_32x32x16_bf16 v[16:31], v[188:191], v[242:245], v[16:31]
	ds_read_b64_tr_b16 v[230:231], v182 offset:45056
	ds_read_b64_tr_b16 v[232:233], v182 offset:47104
	v_exp_f32_e32 v142, v142
	v_exp_f32_e32 v143, v143
	s_waitcnt vmcnt(0)
	ds_write_b128 v180, v[160:163] offset:8192
	s_waitcnt lgkmcnt(11)
	v_mfma_f32_32x32x16_bf16 v[0:15], v[192:195], v[200:203], v[0:15]
	ds_read_b64_tr_b16 v[234:235], v182 offset:45568
	ds_read_b64_tr_b16 v[236:237], v182 offset:47616
	ds_read_b128 v[200:203], v172 offset:0
	v_exp_f32_e32 v144, v144
	v_exp_f32_e32 v145, v145
	s_waitcnt lgkmcnt(11)
	v_mfma_f32_32x32x16_bf16 v[48:63], v[192:195], v[204:207], v[48:63]
	ds_read_b64_tr_b16 v[238:239], v182 offset:46080
	ds_read_b64_tr_b16 v[240:241], v182 offset:48128
	ds_read_b128 v[204:207], v172 offset:8192
	v_exp_f32_e32 v146, v146
	v_exp_f32_e32 v147, v147
	s_waitcnt lgkmcnt(12)
	v_mfma_f32_32x32x16_bf16 v[32:47], v[192:195], v[208:211], v[32:47]
	ds_read_b64_tr_b16 v[242:243], v182 offset:46592
	ds_read_b64_tr_b16 v[244:245], v182 offset:48640
	ds_read_b128 v[208:211], v173 offset:0
	v_exp_f32_e32 v148, v148
	v_exp_f32_e32 v149, v149
	s_waitcnt lgkmcnt(12)
	v_mfma_f32_32x32x16_bf16 v[16:31], v[192:195], v[212:215], v[16:31]
	ds_read_b128 v[212:215], v173 offset:8192
	v_exp_f32_e32 v150, v150
	v_exp_f32_e32 v151, v151
	s_waitcnt lgkmcnt(11)
	v_mfma_f32_32x32x16_bf16 v[0:15], v[196:199], v[230:233], v[0:15]
	ds_read_b128 v[230:233], v174 offset:0
	v_exp_f32_e32 v152, v152
	v_exp_f32_e32 v153, v153
	s_waitcnt lgkmcnt(9)
	v_mfma_f32_32x32x16_bf16 v[48:63], v[196:199], v[234:237], v[48:63]
	ds_read_b128 v[234:237], v174 offset:8192
	v_exp_f32_e32 v154, v154
	v_exp_f32_e32 v155, v155
	s_waitcnt lgkmcnt(7)
	v_mfma_f32_32x32x16_bf16 v[32:47], v[196:199], v[238:241], v[32:47]
	ds_read_b128 v[238:241], v175 offset:0
	v_exp_f32_e32 v156, v156
	v_exp_f32_e32 v157, v157
	s_waitcnt lgkmcnt(5)
	v_mfma_f32_32x32x16_bf16 v[16:31], v[196:199], v[242:245], v[16:31]
	ds_read_b128 v[242:245], v175 offset:8192
	v_exp_f32_e32 v158, v158
	v_exp_f32_e32 v159, v159
	s_barrier
	v_mfma_f32_32x32x16_bf16 v[64:79], v[200:203], v[124:127], 0
	ds_read_b128 v[200:203], v176 offset:0
	v_cvt_pk_bf16_f32 v184, v128, v129
	v_add_f32_e32 v169, v169, v128
	v_add_f32_e32 v219, v219, v129
	global_load_dwordx4 v[246:249], v183, s[98:99]
	v_mfma_f32_32x32x16_bf16 v[80:95], v[204:207], v[124:127], 0
	ds_read_b128 v[204:207], v176 offset:8192
	v_cvt_pk_bf16_f32 v185, v130, v131
	v_add_f32_e32 v222, v222, v130
	v_add_f32_e32 v254, v254, v131
	s_waitcnt lgkmcnt(7)
	v_mfma_f32_32x32x16_bf16 v[64:79], v[208:211], v[120:123], v[64:79]
	ds_read_b128 v[208:211], v177 offset:0
	v_cvt_pk_bf16_f32 v186, v132, v133
	v_add_f32_e32 v169, v169, v132
	v_add_f32_e32 v219, v219, v133
	global_load_dwordx4 v[250:253], v183, s[100:101]
	s_add_u32 s98, s98, 0x150000
	s_addc_u32 s99, s99, 0
	s_add_u32 s100, s100, 0x150000
	s_addc_u32 s101, s101, 0
	s_waitcnt lgkmcnt(7)
	v_mfma_f32_32x32x16_bf16 v[80:95], v[212:215], v[120:123], v[80:95]
	ds_read_b128 v[212:215], v177 offset:8192
	v_cvt_pk_bf16_f32 v187, v134, v135
	v_add_f32_e32 v222, v222, v134
	v_add_f32_e32 v254, v254, v135
	s_waitcnt lgkmcnt(7)
	v_mfma_f32_32x32x16_bf16 v[64:79], v[230:233], v[116:119], v[64:79]
	ds_read_b128 v[230:233], v178 offset:0
	v_cvt_pk_bf16_f32 v188, v136, v137
	v_add_f32_e32 v169, v169, v136
	v_add_f32_e32 v219, v219, v137
	v_permlane32_swap_b32_e32 v184, v186
	global_load_dwordx4 v[164:167], v183, s[0:1] offset:512
	s_waitcnt lgkmcnt(7)
	v_mfma_f32_32x32x16_bf16 v[80:95], v[234:237], v[116:119], v[80:95]
	ds_read_b128 v[234:237], v178 offset:8192
	v_cvt_pk_bf16_f32 v189, v138, v139
	v_add_f32_e32 v222, v222, v138
	v_add_f32_e32 v254, v254, v139
	v_permlane32_swap_b32_e32 v185, v187
	s_waitcnt lgkmcnt(7)
	v_mfma_f32_32x32x16_bf16 v[64:79], v[238:241], v[112:115], v[64:79]
	ds_read_b128 v[238:241], v179 offset:0
	v_cvt_pk_bf16_f32 v190, v140, v141
	v_add_f32_e32 v169, v169, v140
	v_add_f32_e32 v219, v219, v141
	global_load_dwordx4 v[160:163], v183, s[4:5] offset:512
	s_add_u32 s0, s0, 0x150000
	s_addc_u32 s1, s1, 0
	s_add_u32 s4, s4, 0x150000
	s_addc_u32 s5, s5, 0
	s_waitcnt lgkmcnt(7)
	v_mfma_f32_32x32x16_bf16 v[80:95], v[242:245], v[112:115], v[80:95]
	ds_read_b128 v[242:245], v179 offset:8192
	v_cvt_pk_bf16_f32 v191, v142, v143
	v_add_f32_e32 v222, v222, v142
	v_add_f32_e32 v254, v254, v143
	s_waitcnt lgkmcnt(7)
	v_mfma_f32_32x32x16_bf16 v[64:79], v[200:203], v[108:111], v[64:79]
	v_cvt_pk_bf16_f32 v192, v144, v145
	v_add_f32_e32 v169, v169, v144
	v_add_f32_e32 v219, v219, v145
	v_permlane32_swap_b32_e32 v188, v190
	s_waitcnt lgkmcnt(6)
	v_mfma_f32_32x32x16_bf16 v[80:95], v[204:207], v[108:111], v[80:95]
	v_cvt_pk_bf16_f32 v193, v146, v147
	v_add_f32_e32 v222, v222, v146
	v_add_f32_e32 v254, v254, v147
	v_permlane32_swap_b32_e32 v189, v191
	s_waitcnt lgkmcnt(5)
; __device__ __forceinline__ void finishSM(f32x16& p0, f32x16& p1, float alpha, float& l_reg, bf16x8& pa0, bf16x8& pa1, bf16x8& pa2, bf16x8& pa3) {
; #pragma unroll
;   for (int r = 0; r < 16; ++r) p1[r] = __builtin_amdgcn_exp2f(p1[r]);
;   float ps = 0;
; #pragma unroll
;   for (int r = 0; r < 16; ++r) ps += p0[r];
; #pragma unroll
;   for (int r = 0; r < 16; ++r) ps += p1[r];
;   { auto rr = __builtin_amdgcn_permlane32_swap(__float_as_uint(ps), __float_as_uint(ps), false, false);
;     ps = __uint_as_float(rr[0]) + __uint_as_float(rr[1]); }
;   l_reg = l_reg * alpha + ps;
;     ...
;   PK4(p0, 0, pa0); PK4(p0, 8, pa1); PK4(p1, 0, pa2); PK4(p1, 8, pa3);
;     ...
; }
; __device__ __forceinline__ void qkt(f32x16& p0, f32x16& p1, const bf16* Ks, const bf16x8* qr, int r32, int hi) {
;   p0 = f32x16{}; p1 = f32x16{};
; #pragma unroll
;   for (int d0 = 0; d0 < 8; ++d0) { int cb = (d0 * 16 + hi * 8) * 2;
;     bf16x8 b0 = *reinterpret_cast<const bf16x8*>((const char*)Ks + KSWZ(r32, cb));
;     bf16x8 b1 = *reinterpret_cast<const bf16x8*>((const char*)Ks + KSWZ(32 + r32, cb));
;     p0 = __builtin_amdgcn_mfma_f32_32x32x16_bf16(b0, qr[d0], p0, 0, 0, 0);
;     p1 = __builtin_amdgcn_mfma_f32_32x32x16_bf16(b1, qr[d0], p1, 0, 0, 0); }
; }
; __device__ __forceinline__ int v_st(int k, int c) { const int kk = (k & ~0xC) | ((k & 4) << 1) | ((k & 8) >> 1); return ((kk >> 3) * 4 + (c >> 5)) * 512 + ((kk & 7) * 32 + (c & 31)) * 2; }
; __device__ __forceinline__ int v_rd_base(int lane) { return ((lane & 3) << 3) | (((lane >> 2) & 3) << 6) | (((lane >> 4) & 1) << 5) | (((lane >> 5) & 1) << 8); }
; template <int OFF> __device__ __forceinline__ s16x4 tr_read(int vb) {
;   s16x4 r; asm volatile("ds_read_b64_tr_b16 %0, %1 offset:%2" : "=&v"(r) : "v"(vb), "i"(OFF) : "memory"); return r;
; }
; template <int D0> __device__ __forceinline__ void pv_one(f32x16& od, int vb, bf16x8 pa0, bf16x8 pa1, bf16x8 pa2, bf16x8 pa3) {
;   const s16x4 l0 = tr_read<v_rd_off(D0, 0, 0)>(vb), h0 = tr_read<v_rd_off(D0, 0, 1)>(vb), l1 = tr_read<v_rd_off(D0, 1, 0)>(vb), h1 = tr_read<v_rd_off(D0, 1, 1)>(vb);
;   const s16x4 l2 = tr_read<v_rd_off(D0, 2, 0)>(vb), h2 = tr_read<v_rd_off(D0, 2, 1)>(vb), l3 = tr_read<v_rd_off(D0, 3, 0)>(vb), h3 = tr_read<v_rd_off(D0, 3, 1)>(vb);
;   asm volatile("s_waitcnt lgkmcnt(0)" ::: "memory"); SBAR();
;     ...
;   od = __builtin_amdgcn_mfma_f32_32x32x16_bf16(pa0, PK(l0, h0), od, 0, 0, 0);
	v_mfma_f32_32x32x16_bf16 v[64:79], v[208:211], v[104:107], v[64:79]
	v_cvt_pk_bf16_f32 v194, v148, v149
	v_add_f32_e32 v169, v169, v148
	v_add_f32_e32 v219, v219, v149
	s_waitcnt lgkmcnt(4)
	v_mfma_f32_32x32x16_bf16 v[80:95], v[212:215], v[104:107], v[80:95]
	ds_read_b64_tr_b16 v[200:201], v182 offset:49152
	ds_read_b64_tr_b16 v[202:203], v182 offset:51200
	v_cvt_pk_bf16_f32 v195, v150, v151
	v_add_f32_e32 v222, v222, v150
	v_add_f32_e32 v254, v254, v151
	s_waitcnt lgkmcnt(5)
	v_mfma_f32_32x32x16_bf16 v[64:79], v[230:233], v[100:103], v[64:79]
	ds_read_b64_tr_b16 v[204:205], v182 offset:49664
	ds_read_b64_tr_b16 v[206:207], v182 offset:51712
	v_cvt_pk_bf16_f32 v196, v152, v153
	v_add_f32_e32 v169, v169, v152
	v_add_f32_e32 v219, v219, v153
	v_permlane32_swap_b32_e32 v192, v194
	s_waitcnt lgkmcnt(6)
	v_mfma_f32_32x32x16_bf16 v[80:95], v[234:237], v[100:103], v[80:95]
	ds_read_b64_tr_b16 v[208:209], v182 offset:50176
	ds_read_b64_tr_b16 v[210:211], v182 offset:52224
	v_cvt_pk_bf16_f32 v197, v154, v155
	v_add_f32_e32 v222, v222, v154
	v_add_f32_e32 v254, v254, v155
	v_permlane32_swap_b32_e32 v193, v195
	s_waitcnt lgkmcnt(7)
	v_mfma_f32_32x32x16_bf16 v[64:79], v[238:241], v[96:99], v[64:79]
	ds_read_b64_tr_b16 v[212:213], v182 offset:50688
	ds_read_b64_tr_b16 v[214:215], v182 offset:52736
	v_cvt_pk_bf16_f32 v198, v156, v157
	v_add_f32_e32 v169, v169, v156
	v_add_f32_e32 v219, v219, v157
	s_waitcnt lgkmcnt(8)
	v_mfma_f32_32x32x16_bf16 v[80:95], v[242:245], v[96:99], v[80:95]
	ds_read_b64_tr_b16 v[230:231], v182 offset:53248
	ds_read_b64_tr_b16 v[232:233], v182 offset:55296
	v_cvt_pk_bf16_f32 v199, v158, v159
	v_add_f32_e32 v222, v222, v158
	v_add_f32_e32 v254, v254, v159
	v_permlane32_swap_b32_e32 v196, v198
	v_permlane32_swap_b32_e32 v197, v199
	s_waitcnt lgkmcnt(8)
	v_mfma_f32_32x32x16_bf16 v[0:15], v[184:187], v[200:203], v[0:15]
	ds_read_b64_tr_b16 v[234:235], v182 offset:53760
	ds_read_b64_tr_b16 v[236:237], v182 offset:55808
	v_exp_f32_e32 v64, v64
	v_exp_f32_e32 v65, v65
	s_waitcnt lgkmcnt(8)
	v_mfma_f32_32x32x16_bf16 v[48:63], v[184:187], v[204:207], v[48:63]
	ds_read_b64_tr_b16 v[238:239], v182 offset:54272
	ds_read_b64_tr_b16 v[240:241], v182 offset:56320
	v_exp_f32_e32 v66, v66
	v_exp_f32_e32 v67, v67
	s_waitcnt vmcnt(3)
	ds_write_b128 v181, v[246:249] offset:32768
	s_waitcnt lgkmcnt(9)
	v_mfma_f32_32x32x16_bf16 v[32:47], v[184:187], v[208:211], v[32:47]
	ds_read_b64_tr_b16 v[242:243], v182 offset:54784
	ds_read_b64_tr_b16 v[244:245], v182 offset:56832
	v_exp_f32_e32 v68, v68
	v_exp_f32_e32 v69, v69
	s_waitcnt lgkmcnt(9)
	v_mfma_f32_32x32x16_bf16 v[16:31], v[184:187], v[212:215], v[16:31]
	ds_read_b64_tr_b16 v[200:201], v182 offset:57344
	ds_read_b64_tr_b16 v[202:203], v182 offset:59392
	v_exp_f32_e32 v70, v70
	v_exp_f32_e32 v71, v71
	s_waitcnt vmcnt(2)
	ds_write_b128 v181, v[250:253] offset:40960
	s_waitcnt lgkmcnt(10)
	v_mfma_f32_32x32x16_bf16 v[0:15], v[188:191], v[230:233], v[0:15]
	ds_read_b64_tr_b16 v[204:205], v182 offset:57856
	ds_read_b64_tr_b16 v[206:207], v182 offset:59904
	v_exp_f32_e32 v72, v72
	v_exp_f32_e32 v73, v73
	s_waitcnt lgkmcnt(10)
	v_mfma_f32_32x32x16_bf16 v[48:63], v[188:191], v[234:237], v[48:63]
	ds_read_b64_tr_b16 v[208:209], v182 offset:58368
	ds_read_b64_tr_b16 v[210:211], v182 offset:60416
	v_exp_f32_e32 v74, v74
	v_exp_f32_e32 v75, v75
	s_waitcnt vmcnt(1)
	ds_write_b128 v180, v[164:167] offset:16384
	s_waitcnt lgkmcnt(11)
	v_mfma_f32_32x32x16_bf16 v[32:47], v[188:191], v[238:241], v[32:47]
	ds_read_b64_tr_b16 v[212:213], v182 offset:58880
	ds_read_b64_tr_b16 v[214:215], v182 offset:60928
	v_exp_f32_e32 v76, v76
	v_exp_f32_e32 v77, v77
	s_waitcnt lgkmcnt(10)
	v_mfma_f32_32x32x16_bf16 v[16:31], v[188:191], v[242:245], v[16:31]
	ds_read_b64_tr_b16 v[230:231], v182 offset:61440
	ds_read_b64_tr_b16 v[232:233], v182 offset:63488
	v_exp_f32_e32 v78, v78
	v_exp_f32_e32 v79, v79
	s_waitcnt vmcnt(0)
	ds_write_b128 v180, v[160:163] offset:24576
	s_waitcnt lgkmcnt(11)
	v_mfma_f32_32x32x16_bf16 v[0:15], v[192:195], v[200:203], v[0:15]
	ds_read_b64_tr_b16 v[234:235], v182 offset:61952
	ds_read_b64_tr_b16 v[236:237], v182 offset:64000
	ds_read_b128 v[200:203], v172 offset:16384
	v_exp_f32_e32 v80, v80
	v_exp_f32_e32 v81, v81
	s_waitcnt lgkmcnt(11)
	v_mfma_f32_32x32x16_bf16 v[48:63], v[192:195], v[204:207], v[48:63]
	ds_read_b64_tr_b16 v[238:239], v182 offset:62464
	ds_read_b64_tr_b16 v[240:241], v182 offset:64512
	ds_read_b128 v[204:207], v172 offset:24576
	v_exp_f32_e32 v82, v82
	v_exp_f32_e32 v83, v83
	s_waitcnt lgkmcnt(12)
	v_mfma_f32_32x32x16_bf16 v[32:47], v[192:195], v[208:211], v[32:47]
	ds_read_b64_tr_b16 v[242:243], v182 offset:62976
	ds_read_b64_tr_b16 v[244:245], v182 offset:65024
	ds_read_b128 v[208:211], v173 offset:16384
	v_exp_f32_e32 v84, v84
	v_exp_f32_e32 v85, v85
	s_waitcnt lgkmcnt(12)
	v_mfma_f32_32x32x16_bf16 v[16:31], v[192:195], v[212:215], v[16:31]
	ds_read_b128 v[212:215], v173 offset:24576
	v_exp_f32_e32 v86, v86
	v_exp_f32_e32 v87, v87
	s_waitcnt lgkmcnt(11)
	v_mfma_f32_32x32x16_bf16 v[0:15], v[196:199], v[230:233], v[0:15]
	ds_read_b128 v[230:233], v174 offset:16384
	v_exp_f32_e32 v88, v88
	v_exp_f32_e32 v89, v89
	s_waitcnt lgkmcnt(9)
	v_mfma_f32_32x32x16_bf16 v[48:63], v[196:199], v[234:237], v[48:63]
	ds_read_b128 v[234:237], v174 offset:24576
	v_exp_f32_e32 v90, v90
	v_exp_f32_e32 v91, v91
	s_waitcnt lgkmcnt(7)
	v_mfma_f32_32x32x16_bf16 v[32:47], v[196:199], v[238:241], v[32:47]
	ds_read_b128 v[238:241], v175 offset:16384
	v_exp_f32_e32 v92, v92
	v_exp_f32_e32 v93, v93
	s_waitcnt lgkmcnt(5)
	v_mfma_f32_32x32x16_bf16 v[16:31], v[196:199], v[242:245], v[16:31]
	ds_read_b128 v[242:245], v175 offset:24576
	v_exp_f32_e32 v94, v94
	v_exp_f32_e32 v95, v95
	s_barrier
; __device__ __forceinline__ void finishSM(f32x16& p0, f32x16& p1, float alpha, float& l_reg, bf16x8& pa0, bf16x8& pa1, bf16x8& pa2, bf16x8& pa3) {
; #pragma unroll
;   for (int r = 0; r < 16; ++r) p1[r] = __builtin_amdgcn_exp2f(p1[r]);
;   float ps = 0;
; #pragma unroll
;   for (int r = 0; r < 16; ++r) ps += p0[r];
; #pragma unroll
;   for (int r = 0; r < 16; ++r) ps += p1[r];
;   { auto rr = __builtin_amdgcn_permlane32_swap(__float_as_uint(ps), __float_as_uint(ps), false, false);
;     ps = __uint_as_float(rr[0]) + __uint_as_float(rr[1]); }
;   l_reg = l_reg * alpha + ps;
;     ...
;   PK4(p0, 0, pa0); PK4(p0, 8, pa1); PK4(p1, 0, pa2); PK4(p1, 8, pa3);
;     ...
; }
; __device__ __forceinline__ void qkt(f32x16& p0, f32x16& p1, const bf16* Ks, const bf16x8* qr, int r32, int hi) {
;   p0 = f32x16{}; p1 = f32x16{};
; #pragma unroll
;   for (int d0 = 0; d0 < 8; ++d0) { int cb = (d0 * 16 + hi * 8) * 2;
;     bf16x8 b0 = *reinterpret_cast<const bf16x8*>((const char*)Ks + KSWZ(r32, cb));
;     bf16x8 b1 = *reinterpret_cast<const bf16x8*>((const char*)Ks + KSWZ(32 + r32, cb));
;     p0 = __builtin_amdgcn_mfma_f32_32x32x16_bf16(b0, qr[d0], p0, 0, 0, 0);
;     p1 = __builtin_amdgcn_mfma_f32_32x32x16_bf16(b1, qr[d0], p1, 0, 0, 0); }
; }
; __device__ __forceinline__ int v_st(int k, int c) { const int kk = (k & ~0xC) | ((k & 4) << 1) | ((k & 8) >> 1); return ((kk >> 3) * 4 + (c >> 5)) * 512 + ((kk & 7) * 32 + (c & 31)) * 2; }
; __device__ __forceinline__ int v_rd_base(int lane) { return ((lane & 3) << 3) | (((lane >> 2) & 3) << 6) | (((lane >> 4) & 1) << 5) | (((lane >> 5) & 1) << 8); }
; template <int OFF> __device__ __forceinline__ s16x4 tr_read(int vb) {
;   s16x4 r; asm volatile("ds_read_b64_tr_b16 %0, %1 offset:%2" : "=&v"(r) : "v"(vb), "i"(OFF) : "memory"); return r;
; }
; template <int D0> __device__ __forceinline__ void pv_one(f32x16& od, int vb, bf16x8 pa0, bf16x8 pa1, bf16x8 pa2, bf16x8 pa3) {
;   const s16x4 l0 = tr_read<v_rd_off(D0, 0, 0)>(vb), h0 = tr_read<v_rd_off(D0, 0, 1)>(vb), l1 = tr_read<v_rd_off(D0, 1, 0)>(vb), h1 = tr_read<v_rd_off(D0, 1, 1)>(vb);
;   const s16x4 l2 = tr_read<v_rd_off(D0, 2, 0)>(vb), h2 = tr_read<v_rd_off(D0, 2, 1)>(vb), l3 = tr_read<v_rd_off(D0, 3, 0)>(vb), h3 = tr_read<v_rd_off(D0, 3, 1)>(vb);
;   asm volatile("s_waitcnt lgkmcnt(0)" ::: "memory"); SBAR();
;     ...
;   od = __builtin_amdgcn_mfma_f32_32x32x16_bf16(pa0, PK(l0, h0), od, 0, 0, 0);
	s_add_i32 s44, s44, 1
	s_cmp_lt_u32 s44, 63
	s_cbranch_scc1 .Ldense_loop
	v_mfma_f32_32x32x16_bf16 v[128:143], v[200:203], v[124:127], 0
	ds_read_b128 v[200:203], v176 offset:16384
	v_cvt_pk_bf16_f32 v184, v64, v65
	v_add_f32_e32 v169, v169, v64
	v_add_f32_e32 v219, v219, v65
	global_load_dwordx4 v[246:249], v183, s[98:99]
	v_mfma_f32_32x32x16_bf16 v[144:159], v[204:207], v[124:127], 0
	ds_read_b128 v[204:207], v176 offset:24576
	v_cvt_pk_bf16_f32 v185, v66, v67
	v_add_f32_e32 v222, v222, v66
	v_add_f32_e32 v254, v254, v67
	s_waitcnt lgkmcnt(7)
	v_mfma_f32_32x32x16_bf16 v[128:143], v[208:211], v[120:123], v[128:143]
	ds_read_b128 v[208:211], v177 offset:16384
	v_cvt_pk_bf16_f32 v186, v68, v69
	v_add_f32_e32 v169, v169, v68
	v_add_f32_e32 v219, v219, v69
	global_load_dwordx4 v[250:253], v183, s[100:101]
	s_add_u32 s98, s98, 0x150000
	s_addc_u32 s99, s99, 0
	s_add_u32 s100, s100, 0x150000
	s_addc_u32 s101, s101, 0
	s_waitcnt lgkmcnt(7)
	v_mfma_f32_32x32x16_bf16 v[144:159], v[212:215], v[120:123], v[144:159]
	ds_read_b128 v[212:215], v177 offset:24576
	v_cvt_pk_bf16_f32 v187, v70, v71
	v_add_f32_e32 v222, v222, v70
	v_add_f32_e32 v254, v254, v71
	s_waitcnt lgkmcnt(7)
	v_mfma_f32_32x32x16_bf16 v[128:143], v[230:233], v[116:119], v[128:143]
	ds_read_b128 v[230:233], v178 offset:16384
	v_cvt_pk_bf16_f32 v188, v72, v73
	v_add_f32_e32 v169, v169, v72
	v_add_f32_e32 v219, v219, v73
	v_permlane32_swap_b32_e32 v184, v186
	global_load_dwordx4 v[164:167], v183, s[0:1] offset:512
	s_waitcnt lgkmcnt(7)
	v_mfma_f32_32x32x16_bf16 v[144:159], v[234:237], v[116:119], v[144:159]
	ds_read_b128 v[234:237], v178 offset:24576
	v_cvt_pk_bf16_f32 v189, v74, v75
	v_add_f32_e32 v222, v222, v74
	v_add_f32_e32 v254, v254, v75
	v_permlane32_swap_b32_e32 v185, v187
	s_waitcnt lgkmcnt(7)
	v_mfma_f32_32x32x16_bf16 v[128:143], v[238:241], v[112:115], v[128:143]
	ds_read_b128 v[238:241], v179 offset:16384
	v_cvt_pk_bf16_f32 v190, v76, v77
	v_add_f32_e32 v169, v169, v76
	v_add_f32_e32 v219, v219, v77
	global_load_dwordx4 v[160:163], v183, s[4:5] offset:512
	s_add_u32 s0, s0, 0x150000
	s_addc_u32 s1, s1, 0
	s_add_u32 s4, s4, 0x150000
	s_addc_u32 s5, s5, 0
	s_waitcnt lgkmcnt(7)
	v_mfma_f32_32x32x16_bf16 v[144:159], v[242:245], v[112:115], v[144:159]
	ds_read_b128 v[242:245], v179 offset:24576
	v_cvt_pk_bf16_f32 v191, v78, v79
	v_add_f32_e32 v222, v222, v78
	v_add_f32_e32 v254, v254, v79
	s_waitcnt lgkmcnt(7)
	v_mfma_f32_32x32x16_bf16 v[128:143], v[200:203], v[108:111], v[128:143]
	v_cvt_pk_bf16_f32 v192, v80, v81
	v_add_f32_e32 v169, v169, v80
	v_add_f32_e32 v219, v219, v81
	v_permlane32_swap_b32_e32 v188, v190
	s_waitcnt lgkmcnt(6)
	v_mfma_f32_32x32x16_bf16 v[144:159], v[204:207], v[108:111], v[144:159]
	v_cvt_pk_bf16_f32 v193, v82, v83
	v_add_f32_e32 v222, v222, v82
	v_add_f32_e32 v254, v254, v83
	v_permlane32_swap_b32_e32 v189, v191
	s_waitcnt lgkmcnt(5)
	v_mfma_f32_32x32x16_bf16 v[128:143], v[208:211], v[104:107], v[128:143]
	v_cvt_pk_bf16_f32 v194, v84, v85
	v_add_f32_e32 v169, v169, v84
	v_add_f32_e32 v219, v219, v85
	s_waitcnt lgkmcnt(4)
	v_mfma_f32_32x32x16_bf16 v[144:159], v[212:215], v[104:107], v[144:159]
	ds_read_b64_tr_b16 v[200:201], v182 offset:0
	ds_read_b64_tr_b16 v[202:203], v182 offset:2048
	v_cvt_pk_bf16_f32 v195, v86, v87
	v_add_f32_e32 v222, v222, v86
	v_add_f32_e32 v254, v254, v87
	s_waitcnt lgkmcnt(5)
	v_mfma_f32_32x32x16_bf16 v[128:143], v[230:233], v[100:103], v[128:143]
	ds_read_b64_tr_b16 v[204:205], v182 offset:512
	ds_read_b64_tr_b16 v[206:207], v182 offset:2560
	v_cvt_pk_bf16_f32 v196, v88, v89
	v_add_f32_e32 v169, v169, v88
	v_add_f32_e32 v219, v219, v89
	v_permlane32_swap_b32_e32 v192, v194
	s_waitcnt lgkmcnt(6)
	v_mfma_f32_32x32x16_bf16 v[144:159], v[234:237], v[100:103], v[144:159]
	ds_read_b64_tr_b16 v[208:209], v182 offset:1024
	ds_read_b64_tr_b16 v[210:211], v182 offset:3072
	v_cvt_pk_bf16_f32 v197, v90, v91
	v_add_f32_e32 v222, v222, v90
	v_add_f32_e32 v254, v254, v91
	v_permlane32_swap_b32_e32 v193, v195
	s_waitcnt lgkmcnt(7)
	v_mfma_f32_32x32x16_bf16 v[128:143], v[238:241], v[96:99], v[128:143]
	ds_read_b64_tr_b16 v[212:213], v182 offset:1536
	ds_read_b64_tr_b16 v[214:215], v182 offset:3584
	v_cvt_pk_bf16_f32 v198, v92, v93
	v_add_f32_e32 v169, v169, v92
	v_add_f32_e32 v219, v219, v93
	s_waitcnt lgkmcnt(8)
	v_mfma_f32_32x32x16_bf16 v[144:159], v[242:245], v[96:99], v[144:159]
	ds_read_b64_tr_b16 v[230:231], v182 offset:4096
	ds_read_b64_tr_b16 v[232:233], v182 offset:6144
	v_cvt_pk_bf16_f32 v199, v94, v95
	v_add_f32_e32 v222, v222, v94
	v_add_f32_e32 v254, v254, v95
	v_permlane32_swap_b32_e32 v196, v198
	v_permlane32_swap_b32_e32 v197, v199
	s_waitcnt lgkmcnt(8)
	v_mfma_f32_32x32x16_bf16 v[0:15], v[184:187], v[200:203], v[0:15]
	ds_read_b64_tr_b16 v[234:235], v182 offset:4608
	ds_read_b64_tr_b16 v[236:237], v182 offset:6656
	v_exp_f32_e32 v128, v128
	v_exp_f32_e32 v129, v129
	s_waitcnt lgkmcnt(8)
	v_mfma_f32_32x32x16_bf16 v[48:63], v[184:187], v[204:207], v[48:63]
	ds_read_b64_tr_b16 v[238:239], v182 offset:5120
	ds_read_b64_tr_b16 v[240:241], v182 offset:7168
	v_exp_f32_e32 v130, v130
	v_exp_f32_e32 v131, v131
	s_waitcnt vmcnt(3)
	ds_write_b128 v181, v[246:249] offset:49152
	s_waitcnt lgkmcnt(9)
	v_mfma_f32_32x32x16_bf16 v[32:47], v[184:187], v[208:211], v[32:47]
	ds_read_b64_tr_b16 v[242:243], v182 offset:5632
	ds_read_b64_tr_b16 v[244:245], v182 offset:7680
	v_exp_f32_e32 v132, v132
	v_exp_f32_e32 v133, v133
	s_waitcnt lgkmcnt(9)
	v_mfma_f32_32x32x16_bf16 v[16:31], v[184:187], v[212:215], v[16:31]
	ds_read_b64_tr_b16 v[200:201], v182 offset:8192
	ds_read_b64_tr_b16 v[202:203], v182 offset:10240
	v_exp_f32_e32 v134, v134
	v_exp_f32_e32 v135, v135
	s_waitcnt vmcnt(2)
; __device__ __forceinline__ void finishSM(f32x16& p0, f32x16& p1, float alpha, float& l_reg, bf16x8& pa0, bf16x8& pa1, bf16x8& pa2, bf16x8& pa3) {
; #pragma unroll
;   for (int r = 0; r < 16; ++r) p1[r] = __builtin_amdgcn_exp2f(p1[r]);
;   float ps = 0;
; #pragma unroll
;   for (int r = 0; r < 16; ++r) ps += p0[r];
; #pragma unroll
;   for (int r = 0; r < 16; ++r) ps += p1[r];
;   { auto rr = __builtin_amdgcn_permlane32_swap(__float_as_uint(ps), __float_as_uint(ps), false, false);
;     ps = __uint_as_float(rr[0]) + __uint_as_float(rr[1]); }
;   l_reg = l_reg * alpha + ps;
;     ...
;   PK4(p0, 0, pa0); PK4(p0, 8, pa1); PK4(p1, 0, pa2); PK4(p1, 8, pa3);
;     ...
; }
; __device__ __forceinline__ void qkt(f32x16& p0, f32x16& p1, const bf16* Ks, const bf16x8* qr, int r32, int hi) {
;   p0 = f32x16{}; p1 = f32x16{};
; #pragma unroll
;   for (int d0 = 0; d0 < 8; ++d0) { int cb = (d0 * 16 + hi * 8) * 2;
;     bf16x8 b0 = *reinterpret_cast<const bf16x8*>((const char*)Ks + KSWZ(r32, cb));
;     bf16x8 b1 = *reinterpret_cast<const bf16x8*>((const char*)Ks + KSWZ(32 + r32, cb));
;     p0 = __builtin_amdgcn_mfma_f32_32x32x16_bf16(b0, qr[d0], p0, 0, 0, 0);
;     p1 = __builtin_amdgcn_mfma_f32_32x32x16_bf16(b1, qr[d0], p1, 0, 0, 0); }
; }
; __device__ __forceinline__ int v_st(int k, int c) { const int kk = (k & ~0xC) | ((k & 4) << 1) | ((k & 8) >> 1); return ((kk >> 3) * 4 + (c >> 5)) * 512 + ((kk & 7) * 32 + (c & 31)) * 2; }
; __device__ __forceinline__ int v_rd_base(int lane) { return ((lane & 3) << 3) | (((lane >> 2) & 3) << 6) | (((lane >> 4) & 1) << 5) | (((lane >> 5) & 1) << 8); }
; template <int OFF> __device__ __forceinline__ s16x4 tr_read(int vb) {
;   s16x4 r; asm volatile("ds_read_b64_tr_b16 %0, %1 offset:%2" : "=&v"(r) : "v"(vb), "i"(OFF) : "memory"); return r;
; }
; template <int D0> __device__ __forceinline__ void pv_one(f32x16& od, int vb, bf16x8 pa0, bf16x8 pa1, bf16x8 pa2, bf16x8 pa3) {
;   const s16x4 l0 = tr_read<v_rd_off(D0, 0, 0)>(vb), h0 = tr_read<v_rd_off(D0, 0, 1)>(vb), l1 = tr_read<v_rd_off(D0, 1, 0)>(vb), h1 = tr_read<v_rd_off(D0, 1, 1)>(vb);
;   const s16x4 l2 = tr_read<v_rd_off(D0, 2, 0)>(vb), h2 = tr_read<v_rd_off(D0, 2, 1)>(vb), l3 = tr_read<v_rd_off(D0, 3, 0)>(vb), h3 = tr_read<v_rd_off(D0, 3, 1)>(vb);
;   asm volatile("s_waitcnt lgkmcnt(0)" ::: "memory"); SBAR();
;     ...
;   od = __builtin_amdgcn_mfma_f32_32x32x16_bf16(pa0, PK(l0, h0), od, 0, 0, 0);
	ds_write_b128 v181, v[250:253] offset:57344
	s_waitcnt lgkmcnt(10)
	v_mfma_f32_32x32x16_bf16 v[0:15], v[188:191], v[230:233], v[0:15]
	ds_read_b64_tr_b16 v[204:205], v182 offset:8704
	ds_read_b64_tr_b16 v[206:207], v182 offset:10752
	v_exp_f32_e32 v136, v136
	v_exp_f32_e32 v137, v137
	s_waitcnt lgkmcnt(10)
	v_mfma_f32_32x32x16_bf16 v[48:63], v[188:191], v[234:237], v[48:63]
	ds_read_b64_tr_b16 v[208:209], v182 offset:9216
	ds_read_b64_tr_b16 v[210:211], v182 offset:11264
	v_exp_f32_e32 v138, v138
	v_exp_f32_e32 v139, v139
	s_waitcnt vmcnt(1)
	ds_write_b128 v180, v[164:167] offset:32768
	s_waitcnt lgkmcnt(11)
	v_mfma_f32_32x32x16_bf16 v[32:47], v[188:191], v[238:241], v[32:47]
	ds_read_b64_tr_b16 v[212:213], v182 offset:9728
	ds_read_b64_tr_b16 v[214:215], v182 offset:11776
	v_exp_f32_e32 v140, v140
	v_exp_f32_e32 v141, v141
	s_waitcnt lgkmcnt(10)
	v_mfma_f32_32x32x16_bf16 v[16:31], v[188:191], v[242:245], v[16:31]
	ds_read_b64_tr_b16 v[230:231], v182 offset:12288
	ds_read_b64_tr_b16 v[232:233], v182 offset:14336
	v_exp_f32_e32 v142, v142
	v_exp_f32_e32 v143, v143
	s_waitcnt vmcnt(0)
	ds_write_b128 v180, v[160:163] offset:40960
	s_waitcnt lgkmcnt(11)
	v_mfma_f32_32x32x16_bf16 v[0:15], v[192:195], v[200:203], v[0:15]
	ds_read_b64_tr_b16 v[234:235], v182 offset:12800
	ds_read_b64_tr_b16 v[236:237], v182 offset:14848
	ds_read_b128 v[200:203], v172 offset:32768
	v_exp_f32_e32 v144, v144
	v_exp_f32_e32 v145, v145
	s_waitcnt lgkmcnt(11)
	v_mfma_f32_32x32x16_bf16 v[48:63], v[192:195], v[204:207], v[48:63]
	ds_read_b64_tr_b16 v[238:239], v182 offset:13312
	ds_read_b64_tr_b16 v[240:241], v182 offset:15360
	ds_read_b128 v[204:207], v172 offset:40960
	v_exp_f32_e32 v146, v146
	v_exp_f32_e32 v147, v147
	s_waitcnt lgkmcnt(12)
	v_mfma_f32_32x32x16_bf16 v[32:47], v[192:195], v[208:211], v[32:47]
	ds_read_b64_tr_b16 v[242:243], v182 offset:13824
	ds_read_b64_tr_b16 v[244:245], v182 offset:15872
	ds_read_b128 v[208:211], v173 offset:32768
	v_exp_f32_e32 v148, v148
	v_exp_f32_e32 v149, v149
	s_waitcnt lgkmcnt(12)
	v_mfma_f32_32x32x16_bf16 v[16:31], v[192:195], v[212:215], v[16:31]
	ds_read_b128 v[212:215], v173 offset:40960
	v_exp_f32_e32 v150, v150
	v_exp_f32_e32 v151, v151
	s_waitcnt lgkmcnt(11)
	v_mfma_f32_32x32x16_bf16 v[0:15], v[196:199], v[230:233], v[0:15]
	ds_read_b128 v[230:233], v174 offset:32768
	v_exp_f32_e32 v152, v152
	v_exp_f32_e32 v153, v153
	s_waitcnt lgkmcnt(9)
	v_mfma_f32_32x32x16_bf16 v[48:63], v[196:199], v[234:237], v[48:63]
	ds_read_b128 v[234:237], v174 offset:40960
	v_exp_f32_e32 v154, v154
	v_exp_f32_e32 v155, v155
	s_waitcnt lgkmcnt(7)
	v_mfma_f32_32x32x16_bf16 v[32:47], v[196:199], v[238:241], v[32:47]
	ds_read_b128 v[238:241], v175 offset:32768
	v_exp_f32_e32 v156, v156
	v_exp_f32_e32 v157, v157
	s_waitcnt lgkmcnt(5)
	v_mfma_f32_32x32x16_bf16 v[16:31], v[196:199], v[242:245], v[16:31]
	ds_read_b128 v[242:245], v175 offset:40960
	v_exp_f32_e32 v158, v158
	v_exp_f32_e32 v159, v159
	s_barrier
	v_mfma_f32_32x32x16_bf16 v[64:79], v[200:203], v[124:127], 0
	ds_read_b128 v[200:203], v176 offset:32768
	v_cvt_pk_bf16_f32 v184, v128, v129
	v_add_f32_e32 v169, v169, v128
	v_add_f32_e32 v219, v219, v129
	global_load_dwordx4 v[164:167], v183, s[0:1] offset:512
	v_mfma_f32_32x32x16_bf16 v[80:95], v[204:207], v[124:127], 0
	ds_read_b128 v[204:207], v176 offset:40960
	v_cvt_pk_bf16_f32 v185, v130, v131
	v_add_f32_e32 v222, v222, v130
	v_add_f32_e32 v254, v254, v131
	s_waitcnt lgkmcnt(7)
	v_mfma_f32_32x32x16_bf16 v[64:79], v[208:211], v[120:123], v[64:79]
	ds_read_b128 v[208:211], v177 offset:32768
	v_cvt_pk_bf16_f32 v186, v132, v133
	v_add_f32_e32 v169, v169, v132
	v_add_f32_e32 v219, v219, v133
	global_load_dwordx4 v[160:163], v183, s[4:5] offset:512
	s_add_u32 s0, s0, 0x150000
	s_addc_u32 s1, s1, 0
	s_add_u32 s4, s4, 0x150000
	s_addc_u32 s5, s5, 0
	s_waitcnt lgkmcnt(7)
	v_mfma_f32_32x32x16_bf16 v[80:95], v[212:215], v[120:123], v[80:95]
	ds_read_b128 v[212:215], v177 offset:40960
	v_cvt_pk_bf16_f32 v187, v134, v135
	v_add_f32_e32 v222, v222, v134
	v_add_f32_e32 v254, v254, v135
	s_waitcnt lgkmcnt(7)
	v_mfma_f32_32x32x16_bf16 v[64:79], v[230:233], v[116:119], v[64:79]
	ds_read_b128 v[230:233], v178 offset:32768
	v_cvt_pk_bf16_f32 v188, v136, v137
	v_add_f32_e32 v169, v169, v136
	v_add_f32_e32 v219, v219, v137
	v_permlane32_swap_b32_e32 v184, v186
	s_waitcnt lgkmcnt(7)
	v_mfma_f32_32x32x16_bf16 v[80:95], v[234:237], v[116:119], v[80:95]
	ds_read_b128 v[234:237], v178 offset:40960
	v_cvt_pk_bf16_f32 v189, v138, v139
	v_add_f32_e32 v222, v222, v138
	v_add_f32_e32 v254, v254, v139
	v_permlane32_swap_b32_e32 v185, v187
	s_waitcnt lgkmcnt(7)
	v_mfma_f32_32x32x16_bf16 v[64:79], v[238:241], v[112:115], v[64:79]
	ds_read_b128 v[238:241], v179 offset:32768
	v_cvt_pk_bf16_f32 v190, v140, v141
	v_add_f32_e32 v169, v169, v140
	v_add_f32_e32 v219, v219, v141
	s_waitcnt lgkmcnt(7)
	v_mfma_f32_32x32x16_bf16 v[80:95], v[242:245], v[112:115], v[80:95]
	ds_read_b128 v[242:245], v179 offset:40960
	v_cvt_pk_bf16_f32 v191, v142, v143
	v_add_f32_e32 v222, v222, v142
	v_add_f32_e32 v254, v254, v143
	s_waitcnt lgkmcnt(7)
	v_mfma_f32_32x32x16_bf16 v[64:79], v[200:203], v[108:111], v[64:79]
	v_cvt_pk_bf16_f32 v192, v144, v145
	v_add_f32_e32 v169, v169, v144
	v_add_f32_e32 v219, v219, v145
	v_permlane32_swap_b32_e32 v188, v190
	s_waitcnt lgkmcnt(6)
	v_mfma_f32_32x32x16_bf16 v[80:95], v[204:207], v[108:111], v[80:95]
	v_cvt_pk_bf16_f32 v193, v146, v147
	v_add_f32_e32 v222, v222, v146
	v_add_f32_e32 v254, v254, v147
	v_permlane32_swap_b32_e32 v189, v191
	s_waitcnt lgkmcnt(5)
; __device__ __forceinline__ void finishSM(f32x16& p0, f32x16& p1, float alpha, float& l_reg, bf16x8& pa0, bf16x8& pa1, bf16x8& pa2, bf16x8& pa3) {
; #pragma unroll
;   for (int r = 0; r < 16; ++r) p1[r] = __builtin_amdgcn_exp2f(p1[r]);
;   float ps = 0;
; #pragma unroll
;   for (int r = 0; r < 16; ++r) ps += p0[r];
; #pragma unroll
;   for (int r = 0; r < 16; ++r) ps += p1[r];
;   { auto rr = __builtin_amdgcn_permlane32_swap(__float_as_uint(ps), __float_as_uint(ps), false, false);
;     ps = __uint_as_float(rr[0]) + __uint_as_float(rr[1]); }
;   l_reg = l_reg * alpha + ps;
;     ...
;   PK4(p0, 0, pa0); PK4(p0, 8, pa1); PK4(p1, 0, pa2); PK4(p1, 8, pa3);
;     ...
; }
; __device__ __forceinline__ void qkt(f32x16& p0, f32x16& p1, const bf16* Ks, const bf16x8* qr, int r32, int hi) {
;   p0 = f32x16{}; p1 = f32x16{};
; #pragma unroll
;   for (int d0 = 0; d0 < 8; ++d0) { int cb = (d0 * 16 + hi * 8) * 2;
;     bf16x8 b0 = *reinterpret_cast<const bf16x8*>((const char*)Ks + KSWZ(r32, cb));
;     bf16x8 b1 = *reinterpret_cast<const bf16x8*>((const char*)Ks + KSWZ(32 + r32, cb));
;     p0 = __builtin_amdgcn_mfma_f32_32x32x16_bf16(b0, qr[d0], p0, 0, 0, 0);
;     p1 = __builtin_amdgcn_mfma_f32_32x32x16_bf16(b1, qr[d0], p1, 0, 0, 0); }
; }
; __device__ __forceinline__ int v_st(int k, int c) { const int kk = (k & ~0xC) | ((k & 4) << 1) | ((k & 8) >> 1); return ((kk >> 3) * 4 + (c >> 5)) * 512 + ((kk & 7) * 32 + (c & 31)) * 2; }
; __device__ __forceinline__ int v_rd_base(int lane) { return ((lane & 3) << 3) | (((lane >> 2) & 3) << 6) | (((lane >> 4) & 1) << 5) | (((lane >> 5) & 1) << 8); }
; template <int OFF> __device__ __forceinline__ s16x4 tr_read(int vb) {
;   s16x4 r; asm volatile("ds_read_b64_tr_b16 %0, %1 offset:%2" : "=&v"(r) : "v"(vb), "i"(OFF) : "memory"); return r;
; }
; template <int D0> __device__ __forceinline__ void pv_one(f32x16& od, int vb, bf16x8 pa0, bf16x8 pa1, bf16x8 pa2, bf16x8 pa3) {
;   const s16x4 l0 = tr_read<v_rd_off(D0, 0, 0)>(vb), h0 = tr_read<v_rd_off(D0, 0, 1)>(vb), l1 = tr_read<v_rd_off(D0, 1, 0)>(vb), h1 = tr_read<v_rd_off(D0, 1, 1)>(vb);
;   const s16x4 l2 = tr_read<v_rd_off(D0, 2, 0)>(vb), h2 = tr_read<v_rd_off(D0, 2, 1)>(vb), l3 = tr_read<v_rd_off(D0, 3, 0)>(vb), h3 = tr_read<v_rd_off(D0, 3, 1)>(vb);
;   asm volatile("s_waitcnt lgkmcnt(0)" ::: "memory"); SBAR();
;     ...
;   od = __builtin_amdgcn_mfma_f32_32x32x16_bf16(pa0, PK(l0, h0), od, 0, 0, 0);
	v_mfma_f32_32x32x16_bf16 v[64:79], v[208:211], v[104:107], v[64:79]
	v_cvt_pk_bf16_f32 v194, v148, v149
	v_add_f32_e32 v169, v169, v148
	v_add_f32_e32 v219, v219, v149
	s_waitcnt lgkmcnt(4)
	v_mfma_f32_32x32x16_bf16 v[80:95], v[212:215], v[104:107], v[80:95]
	ds_read_b64_tr_b16 v[200:201], v182 offset:16384
	ds_read_b64_tr_b16 v[202:203], v182 offset:18432
	v_cvt_pk_bf16_f32 v195, v150, v151
	v_add_f32_e32 v222, v222, v150
	v_add_f32_e32 v254, v254, v151
	s_waitcnt lgkmcnt(5)
	v_mfma_f32_32x32x16_bf16 v[64:79], v[230:233], v[100:103], v[64:79]
	ds_read_b64_tr_b16 v[204:205], v182 offset:16896
	ds_read_b64_tr_b16 v[206:207], v182 offset:18944
	v_cvt_pk_bf16_f32 v196, v152, v153
	v_add_f32_e32 v169, v169, v152
	v_add_f32_e32 v219, v219, v153
	v_permlane32_swap_b32_e32 v192, v194
	s_waitcnt lgkmcnt(6)
	v_mfma_f32_32x32x16_bf16 v[80:95], v[234:237], v[100:103], v[80:95]
	ds_read_b64_tr_b16 v[208:209], v182 offset:17408
	ds_read_b64_tr_b16 v[210:211], v182 offset:19456
	v_cvt_pk_bf16_f32 v197, v154, v155
	v_add_f32_e32 v222, v222, v154
	v_add_f32_e32 v254, v254, v155
	v_permlane32_swap_b32_e32 v193, v195
	s_waitcnt lgkmcnt(7)
	v_mfma_f32_32x32x16_bf16 v[64:79], v[238:241], v[96:99], v[64:79]
	ds_read_b64_tr_b16 v[212:213], v182 offset:17920
	ds_read_b64_tr_b16 v[214:215], v182 offset:19968
	v_cvt_pk_bf16_f32 v198, v156, v157
	v_add_f32_e32 v169, v169, v156
	v_add_f32_e32 v219, v219, v157
	s_waitcnt lgkmcnt(8)
	v_mfma_f32_32x32x16_bf16 v[80:95], v[242:245], v[96:99], v[80:95]
	ds_read_b64_tr_b16 v[230:231], v182 offset:20480
	ds_read_b64_tr_b16 v[232:233], v182 offset:22528
	v_cvt_pk_bf16_f32 v199, v158, v159
	v_add_f32_e32 v222, v222, v158
	v_add_f32_e32 v254, v254, v159
	v_permlane32_swap_b32_e32 v196, v198
	v_permlane32_swap_b32_e32 v197, v199
	s_waitcnt lgkmcnt(8)
	v_mfma_f32_32x32x16_bf16 v[0:15], v[184:187], v[200:203], v[0:15]
	ds_read_b64_tr_b16 v[234:235], v182 offset:20992
	ds_read_b64_tr_b16 v[236:237], v182 offset:23040
	v_exp_f32_e32 v64, v64
	v_exp_f32_e32 v65, v65
	s_waitcnt lgkmcnt(8)
	v_mfma_f32_32x32x16_bf16 v[48:63], v[184:187], v[204:207], v[48:63]
	ds_read_b64_tr_b16 v[238:239], v182 offset:21504
	ds_read_b64_tr_b16 v[240:241], v182 offset:23552
	v_exp_f32_e32 v66, v66
	v_exp_f32_e32 v67, v67
	s_waitcnt vmcnt(1)
	ds_write_b128 v180, v[164:167] offset:49152
	s_waitcnt lgkmcnt(9)
	v_mfma_f32_32x32x16_bf16 v[32:47], v[184:187], v[208:211], v[32:47]
	ds_read_b64_tr_b16 v[242:243], v182 offset:22016
	ds_read_b64_tr_b16 v[244:245], v182 offset:24064
	v_exp_f32_e32 v68, v68
	v_exp_f32_e32 v69, v69
	s_waitcnt lgkmcnt(9)
	v_mfma_f32_32x32x16_bf16 v[16:31], v[184:187], v[212:215], v[16:31]
	ds_read_b64_tr_b16 v[200:201], v182 offset:24576
	ds_read_b64_tr_b16 v[202:203], v182 offset:26624
	v_exp_f32_e32 v70, v70
	v_exp_f32_e32 v71, v71
	s_waitcnt vmcnt(0)
	ds_write_b128 v180, v[160:163] offset:57344
	s_waitcnt lgkmcnt(10)
	v_mfma_f32_32x32x16_bf16 v[0:15], v[188:191], v[230:233], v[0:15]
	ds_read_b64_tr_b16 v[204:205], v182 offset:25088
	ds_read_b64_tr_b16 v[206:207], v182 offset:27136
	v_exp_f32_e32 v72, v72
	v_exp_f32_e32 v73, v73
	s_waitcnt lgkmcnt(10)
	v_mfma_f32_32x32x16_bf16 v[48:63], v[188:191], v[234:237], v[48:63]
	ds_read_b64_tr_b16 v[208:209], v182 offset:25600
	ds_read_b64_tr_b16 v[210:211], v182 offset:27648
	v_exp_f32_e32 v74, v74
	v_exp_f32_e32 v75, v75
	s_waitcnt lgkmcnt(10)
	v_mfma_f32_32x32x16_bf16 v[32:47], v[188:191], v[238:241], v[32:47]
	ds_read_b64_tr_b16 v[212:213], v182 offset:26112
	ds_read_b64_tr_b16 v[214:215], v182 offset:28160
	v_exp_f32_e32 v76, v76
	v_exp_f32_e32 v77, v77
	s_waitcnt lgkmcnt(9)
	v_mfma_f32_32x32x16_bf16 v[16:31], v[188:191], v[242:245], v[16:31]
	ds_read_b64_tr_b16 v[230:231], v182 offset:28672
	ds_read_b64_tr_b16 v[232:233], v182 offset:30720
	v_exp_f32_e32 v78, v78
	v_exp_f32_e32 v79, v79
	s_waitcnt lgkmcnt(9)
	v_mfma_f32_32x32x16_bf16 v[0:15], v[192:195], v[200:203], v[0:15]
	ds_read_b64_tr_b16 v[234:235], v182 offset:29184
	ds_read_b64_tr_b16 v[236:237], v182 offset:31232
	ds_read_b128 v[200:203], v172 offset:49152
	v_exp_f32_e32 v80, v80
	v_exp_f32_e32 v81, v81
	s_waitcnt lgkmcnt(9)
	v_mfma_f32_32x32x16_bf16 v[48:63], v[192:195], v[204:207], v[48:63]
	ds_read_b64_tr_b16 v[238:239], v182 offset:29696
	ds_read_b64_tr_b16 v[240:241], v182 offset:31744
	ds_read_b128 v[204:207], v172 offset:57344
	v_exp_f32_e32 v82, v82
	v_exp_f32_e32 v83, v83
	s_waitcnt lgkmcnt(10)
	v_mfma_f32_32x32x16_bf16 v[32:47], v[192:195], v[208:211], v[32:47]
	ds_read_b64_tr_b16 v[242:243], v182 offset:30208
	ds_read_b64_tr_b16 v[244:245], v182 offset:32256
	ds_read_b128 v[208:211], v173 offset:49152
	v_exp_f32_e32 v84, v84
	v_exp_f32_e32 v85, v85
	s_waitcnt lgkmcnt(11)
	v_mfma_f32_32x32x16_bf16 v[16:31], v[192:195], v[212:215], v[16:31]
	ds_read_b128 v[212:215], v173 offset:57344
	v_exp_f32_e32 v86, v86
	v_exp_f32_e32 v87, v87
	s_waitcnt lgkmcnt(10)
	v_mfma_f32_32x32x16_bf16 v[0:15], v[196:199], v[230:233], v[0:15]
	ds_read_b128 v[230:233], v174 offset:49152
	v_exp_f32_e32 v88, v88
	v_exp_f32_e32 v89, v89
	s_waitcnt lgkmcnt(9)
	v_mfma_f32_32x32x16_bf16 v[48:63], v[196:199], v[234:237], v[48:63]
	ds_read_b128 v[234:237], v174 offset:57344
	v_exp_f32_e32 v90, v90
	v_exp_f32_e32 v91, v91
	s_waitcnt lgkmcnt(7)
	v_mfma_f32_32x32x16_bf16 v[32:47], v[196:199], v[238:241], v[32:47]
	ds_read_b128 v[238:241], v175 offset:49152
	v_exp_f32_e32 v92, v92
	v_exp_f32_e32 v93, v93
	s_waitcnt lgkmcnt(5)
	v_mfma_f32_32x32x16_bf16 v[16:31], v[196:199], v[242:245], v[16:31]
	ds_read_b128 v[242:245], v175 offset:57344
	v_exp_f32_e32 v94, v94
	v_exp_f32_e32 v95, v95
	s_barrier
; __device__ __forceinline__ void finishSM(f32x16& p0, f32x16& p1, float alpha, float& l_reg, bf16x8& pa0, bf16x8& pa1, bf16x8& pa2, bf16x8& pa3) {
; #pragma unroll
;   for (int r = 0; r < 16; ++r) p1[r] = __builtin_amdgcn_exp2f(p1[r]);
;   float ps = 0;
; #pragma unroll
;   for (int r = 0; r < 16; ++r) ps += p0[r];
; #pragma unroll
;   for (int r = 0; r < 16; ++r) ps += p1[r];
;   { auto rr = __builtin_amdgcn_permlane32_swap(__float_as_uint(ps), __float_as_uint(ps), false, false);
;     ps = __uint_as_float(rr[0]) + __uint_as_float(rr[1]); }
;   l_reg = l_reg * alpha + ps;
;     ...
;   PK4(p0, 0, pa0); PK4(p0, 8, pa1); PK4(p1, 0, pa2); PK4(p1, 8, pa3);
;     ...
; }
; __device__ __forceinline__ void qkt(f32x16& p0, f32x16& p1, const bf16* Ks, const bf16x8* qr, int r32, int hi) {
;   p0 = f32x16{}; p1 = f32x16{};
; #pragma unroll
;   for (int d0 = 0; d0 < 8; ++d0) { int cb = (d0 * 16 + hi * 8) * 2;
;     bf16x8 b0 = *reinterpret_cast<const bf16x8*>((const char*)Ks + KSWZ(r32, cb));
;     bf16x8 b1 = *reinterpret_cast<const bf16x8*>((const char*)Ks + KSWZ(32 + r32, cb));
;     p0 = __builtin_amdgcn_mfma_f32_32x32x16_bf16(b0, qr[d0], p0, 0, 0, 0);
;     p1 = __builtin_amdgcn_mfma_f32_32x32x16_bf16(b1, qr[d0], p1, 0, 0, 0); }
; }
; __device__ __forceinline__ int v_st(int k, int c) { const int kk = (k & ~0xC) | ((k & 4) << 1) | ((k & 8) >> 1); return ((kk >> 3) * 4 + (c >> 5)) * 512 + ((kk & 7) * 32 + (c & 31)) * 2; }
; __device__ __forceinline__ int v_rd_base(int lane) { return ((lane & 3) << 3) | (((lane >> 2) & 3) << 6) | (((lane >> 4) & 1) << 5) | (((lane >> 5) & 1) << 8); }
; template <int OFF> __device__ __forceinline__ s16x4 tr_read(int vb) {
;   s16x4 r; asm volatile("ds_read_b64_tr_b16 %0, %1 offset:%2" : "=&v"(r) : "v"(vb), "i"(OFF) : "memory"); return r;
; }
; template <int D0> __device__ __forceinline__ void pv_one(f32x16& od, int vb, bf16x8 pa0, bf16x8 pa1, bf16x8 pa2, bf16x8 pa3) {
;   const s16x4 l0 = tr_read<v_rd_off(D0, 0, 0)>(vb), h0 = tr_read<v_rd_off(D0, 0, 1)>(vb), l1 = tr_read<v_rd_off(D0, 1, 0)>(vb), h1 = tr_read<v_rd_off(D0, 1, 1)>(vb);
;   const s16x4 l2 = tr_read<v_rd_off(D0, 2, 0)>(vb), h2 = tr_read<v_rd_off(D0, 2, 1)>(vb), l3 = tr_read<v_rd_off(D0, 3, 0)>(vb), h3 = tr_read<v_rd_off(D0, 3, 1)>(vb);
;   asm volatile("s_waitcnt lgkmcnt(0)" ::: "memory"); SBAR();
;     ...
;   od = __builtin_amdgcn_mfma_f32_32x32x16_bf16(pa0, PK(l0, h0), od, 0, 0, 0);
	v_mfma_f32_32x32x16_bf16 v[128:143], v[200:203], v[124:127], 0
	ds_read_b128 v[200:203], v176 offset:49152
	v_cvt_pk_bf16_f32 v184, v64, v65
	v_add_f32_e32 v169, v169, v64
	v_add_f32_e32 v219, v219, v65
	v_mfma_f32_32x32x16_bf16 v[144:159], v[204:207], v[124:127], 0
	ds_read_b128 v[204:207], v176 offset:57344
	v_cvt_pk_bf16_f32 v185, v66, v67
	v_add_f32_e32 v222, v222, v66
	v_add_f32_e32 v254, v254, v67
	s_waitcnt lgkmcnt(7)
	v_mfma_f32_32x32x16_bf16 v[128:143], v[208:211], v[120:123], v[128:143]
	ds_read_b128 v[208:211], v177 offset:49152
	v_cvt_pk_bf16_f32 v186, v68, v69
	v_add_f32_e32 v169, v169, v68
	v_add_f32_e32 v219, v219, v69
	s_waitcnt lgkmcnt(7)
	v_mfma_f32_32x32x16_bf16 v[144:159], v[212:215], v[120:123], v[144:159]
	ds_read_b128 v[212:215], v177 offset:57344
	v_cvt_pk_bf16_f32 v187, v70, v71
	v_add_f32_e32 v222, v222, v70
	v_add_f32_e32 v254, v254, v71
	s_waitcnt lgkmcnt(7)
	v_mfma_f32_32x32x16_bf16 v[128:143], v[230:233], v[116:119], v[128:143]
	ds_read_b128 v[230:233], v178 offset:49152
	v_cvt_pk_bf16_f32 v188, v72, v73
	v_add_f32_e32 v169, v169, v72
	v_add_f32_e32 v219, v219, v73
	v_permlane32_swap_b32_e32 v184, v186
	s_waitcnt lgkmcnt(7)
	v_mfma_f32_32x32x16_bf16 v[144:159], v[234:237], v[116:119], v[144:159]
	ds_read_b128 v[234:237], v178 offset:57344
	v_cvt_pk_bf16_f32 v189, v74, v75
	v_add_f32_e32 v222, v222, v74
	v_add_f32_e32 v254, v254, v75
	v_permlane32_swap_b32_e32 v185, v187
	s_waitcnt lgkmcnt(7)
	v_mfma_f32_32x32x16_bf16 v[128:143], v[238:241], v[112:115], v[128:143]
	ds_read_b128 v[238:241], v179 offset:49152
	v_cvt_pk_bf16_f32 v190, v76, v77
	v_add_f32_e32 v169, v169, v76
	v_add_f32_e32 v219, v219, v77
	s_waitcnt lgkmcnt(7)
	v_mfma_f32_32x32x16_bf16 v[144:159], v[242:245], v[112:115], v[144:159]
	ds_read_b128 v[242:245], v179 offset:57344
	v_cvt_pk_bf16_f32 v191, v78, v79
	v_add_f32_e32 v222, v222, v78
	v_add_f32_e32 v254, v254, v79
	s_waitcnt lgkmcnt(7)
	v_mfma_f32_32x32x16_bf16 v[128:143], v[200:203], v[108:111], v[128:143]
	v_cvt_pk_bf16_f32 v192, v80, v81
	v_add_f32_e32 v169, v169, v80
	v_add_f32_e32 v219, v219, v81
	v_permlane32_swap_b32_e32 v188, v190
	s_waitcnt lgkmcnt(6)
	v_mfma_f32_32x32x16_bf16 v[144:159], v[204:207], v[108:111], v[144:159]
	v_cvt_pk_bf16_f32 v193, v82, v83
	v_add_f32_e32 v222, v222, v82
	v_add_f32_e32 v254, v254, v83
	v_permlane32_swap_b32_e32 v189, v191
	s_waitcnt lgkmcnt(5)
	v_mfma_f32_32x32x16_bf16 v[128:143], v[208:211], v[104:107], v[128:143]
	v_cvt_pk_bf16_f32 v194, v84, v85
	v_add_f32_e32 v169, v169, v84
	v_add_f32_e32 v219, v219, v85
	s_waitcnt lgkmcnt(4)
	v_mfma_f32_32x32x16_bf16 v[144:159], v[212:215], v[104:107], v[144:159]
	ds_read_b64_tr_b16 v[200:201], v182 offset:32768
	ds_read_b64_tr_b16 v[202:203], v182 offset:34816
	v_cvt_pk_bf16_f32 v195, v86, v87
	v_add_f32_e32 v222, v222, v86
	v_add_f32_e32 v254, v254, v87
	s_waitcnt lgkmcnt(5)
	v_mfma_f32_32x32x16_bf16 v[128:143], v[230:233], v[100:103], v[128:143]
	ds_read_b64_tr_b16 v[204:205], v182 offset:33280
	ds_read_b64_tr_b16 v[206:207], v182 offset:35328
	v_cvt_pk_bf16_f32 v196, v88, v89
	v_add_f32_e32 v169, v169, v88
	v_add_f32_e32 v219, v219, v89
	v_permlane32_swap_b32_e32 v192, v194
	s_waitcnt lgkmcnt(6)
	v_mfma_f32_32x32x16_bf16 v[144:159], v[234:237], v[100:103], v[144:159]
	ds_read_b64_tr_b16 v[208:209], v182 offset:33792
	ds_read_b64_tr_b16 v[210:211], v182 offset:35840
	v_cvt_pk_bf16_f32 v197, v90, v91
	v_add_f32_e32 v222, v222, v90
	v_add_f32_e32 v254, v254, v91
	v_permlane32_swap_b32_e32 v193, v195
	s_waitcnt lgkmcnt(7)
	v_mfma_f32_32x32x16_bf16 v[128:143], v[238:241], v[96:99], v[128:143]
	ds_read_b64_tr_b16 v[212:213], v182 offset:34304
	ds_read_b64_tr_b16 v[214:215], v182 offset:36352
	v_cvt_pk_bf16_f32 v198, v92, v93
	v_add_f32_e32 v169, v169, v92
	v_add_f32_e32 v219, v219, v93
	s_waitcnt lgkmcnt(8)
	v_mfma_f32_32x32x16_bf16 v[144:159], v[242:245], v[96:99], v[144:159]
	ds_read_b64_tr_b16 v[230:231], v182 offset:36864
	ds_read_b64_tr_b16 v[232:233], v182 offset:38912
	v_cvt_pk_bf16_f32 v199, v94, v95
	v_add_f32_e32 v222, v222, v94
	v_add_f32_e32 v254, v254, v95
	v_permlane32_swap_b32_e32 v196, v198
	v_permlane32_swap_b32_e32 v197, v199
	s_waitcnt lgkmcnt(8)
	v_mfma_f32_32x32x16_bf16 v[0:15], v[184:187], v[200:203], v[0:15]
	ds_read_b64_tr_b16 v[234:235], v182 offset:37376
	ds_read_b64_tr_b16 v[236:237], v182 offset:39424
	v_exp_f32_e32 v128, v128
	v_exp_f32_e32 v129, v129
	s_waitcnt lgkmcnt(8)
	v_mfma_f32_32x32x16_bf16 v[48:63], v[184:187], v[204:207], v[48:63]
	ds_read_b64_tr_b16 v[238:239], v182 offset:37888
	ds_read_b64_tr_b16 v[240:241], v182 offset:39936
	v_exp_f32_e32 v130, v130
	v_exp_f32_e32 v131, v131
	s_waitcnt lgkmcnt(8)
	v_mfma_f32_32x32x16_bf16 v[32:47], v[184:187], v[208:211], v[32:47]
	ds_read_b64_tr_b16 v[242:243], v182 offset:38400
	ds_read_b64_tr_b16 v[244:245], v182 offset:40448
	v_exp_f32_e32 v132, v132
	v_exp_f32_e32 v133, v133
	s_waitcnt lgkmcnt(8)
	v_mfma_f32_32x32x16_bf16 v[16:31], v[184:187], v[212:215], v[16:31]
	ds_read_b64_tr_b16 v[200:201], v182 offset:40960
	ds_read_b64_tr_b16 v[202:203], v182 offset:43008
	v_exp_f32_e32 v134, v134
	v_exp_f32_e32 v135, v135
	s_waitcnt lgkmcnt(8)
	v_mfma_f32_32x32x16_bf16 v[0:15], v[188:191], v[230:233], v[0:15]
	ds_read_b64_tr_b16 v[204:205], v182 offset:41472
	ds_read_b64_tr_b16 v[206:207], v182 offset:43520
	v_exp_f32_e32 v136, v136
	v_exp_f32_e32 v137, v137
	s_waitcnt lgkmcnt(8)
	v_mfma_f32_32x32x16_bf16 v[48:63], v[188:191], v[234:237], v[48:63]
	ds_read_b64_tr_b16 v[208:209], v182 offset:41984
	ds_read_b64_tr_b16 v[210:211], v182 offset:44032
	v_exp_f32_e32 v138, v138
	v_exp_f32_e32 v139, v139
	s_waitcnt lgkmcnt(8)
; #define SBAR() __builtin_amdgcn_sched_barrier(0)
; template <int D0> __device__ __forceinline__ void pv_one(f32x16& od, int vb, bf16x8 pa0, bf16x8 pa1, bf16x8 pa2, bf16x8 pa3) {
;   const s16x4 l0 = tr_read<v_rd_off(D0, 0, 0)>(vb), h0 = tr_read<v_rd_off(D0, 0, 1)>(vb), l1 = tr_read<v_rd_off(D0, 1, 0)>(vb), h1 = tr_read<v_rd_off(D0, 1, 1)>(vb);
;   const s16x4 l2 = tr_read<v_rd_off(D0, 2, 0)>(vb), h2 = tr_read<v_rd_off(D0, 2, 1)>(vb), l3 = tr_read<v_rd_off(D0, 3, 0)>(vb), h3 = tr_read<v_rd_off(D0, 3, 1)>(vb);
;   asm volatile("s_waitcnt lgkmcnt(0)" ::: "memory"); SBAR();
;     ...
;   od = __builtin_amdgcn_mfma_f32_32x32x16_bf16(pa0, PK(l0, h0), od, 0, 0, 0);
;   od = __builtin_amdgcn_mfma_f32_32x32x16_bf16(pa1, PK(l1, h1), od, 0, 0, 0);
;   od = __builtin_amdgcn_mfma_f32_32x32x16_bf16(pa2, PK(l2, h2), od, 0, 0, 0);
;   od = __builtin_amdgcn_mfma_f32_32x32x16_bf16(pa3, PK(l3, h3), od, 0, 0, 0);
;     ...
; }
; __device__ __forceinline__ void pv_d0(f32x16* o, int vb, bf16x8 pa0, bf16x8 pa1, bf16x8 pa2, bf16x8 pa3) {
;   pv_one<0>(o[0], vb, pa0, pa1, pa2, pa3); pv_one<1>(o[1], vb, pa0, pa1, pa2, pa3); pv_one<2>(o[2], vb, pa0, pa1, pa2, pa3); pv_one<3>(o[3], vb, pa0, pa1, pa2, pa3);
	v_mfma_f32_32x32x16_bf16 v[32:47], v[188:191], v[238:241], v[32:47]
	ds_read_b64_tr_b16 v[212:213], v182 offset:42496
	ds_read_b64_tr_b16 v[214:215], v182 offset:44544
	v_exp_f32_e32 v140, v140
	v_exp_f32_e32 v141, v141
	s_waitcnt lgkmcnt(8)
	v_mfma_f32_32x32x16_bf16 v[16:31], v[188:191], v[242:245], v[16:31]
	ds_read_b64_tr_b16 v[230:231], v182 offset:45056
	ds_read_b64_tr_b16 v[232:233], v182 offset:47104
	v_exp_f32_e32 v142, v142
	v_exp_f32_e32 v143, v143
	s_waitcnt lgkmcnt(8)
	v_mfma_f32_32x32x16_bf16 v[0:15], v[192:195], v[200:203], v[0:15]
	ds_read_b64_tr_b16 v[234:235], v182 offset:45568
	ds_read_b64_tr_b16 v[236:237], v182 offset:47616
	v_exp_f32_e32 v144, v144
	v_exp_f32_e32 v145, v145
	s_waitcnt lgkmcnt(8)
	v_mfma_f32_32x32x16_bf16 v[48:63], v[192:195], v[204:207], v[48:63]
	ds_read_b64_tr_b16 v[238:239], v182 offset:46080
	ds_read_b64_tr_b16 v[240:241], v182 offset:48128
	v_exp_f32_e32 v146, v146
	v_exp_f32_e32 v147, v147
	s_waitcnt lgkmcnt(8)
	v_mfma_f32_32x32x16_bf16 v[32:47], v[192:195], v[208:211], v[32:47]
	ds_read_b64_tr_b16 v[242:243], v182 offset:46592
	ds_read_b64_tr_b16 v[244:245], v182 offset:48640
	v_exp_f32_e32 v148, v148
	v_exp_f32_e32 v149, v149
	s_waitcnt lgkmcnt(8)
	v_mfma_f32_32x32x16_bf16 v[16:31], v[192:195], v[212:215], v[16:31]
	v_exp_f32_e32 v150, v150
	v_exp_f32_e32 v151, v151
	s_waitcnt lgkmcnt(6)
	v_mfma_f32_32x32x16_bf16 v[0:15], v[196:199], v[230:233], v[0:15]
	v_exp_f32_e32 v152, v152
	v_exp_f32_e32 v153, v153
	s_waitcnt lgkmcnt(4)
	v_mfma_f32_32x32x16_bf16 v[48:63], v[196:199], v[234:237], v[48:63]
	v_exp_f32_e32 v154, v154
	v_exp_f32_e32 v155, v155
	s_waitcnt lgkmcnt(2)
	v_mfma_f32_32x32x16_bf16 v[32:47], v[196:199], v[238:241], v[32:47]
	v_exp_f32_e32 v156, v156
	v_exp_f32_e32 v157, v157
	s_waitcnt lgkmcnt(0)
	v_mfma_f32_32x32x16_bf16 v[16:31], v[196:199], v[242:245], v[16:31]
	v_exp_f32_e32 v158, v158
	v_exp_f32_e32 v159, v159
	s_waitcnt lgkmcnt(0)
	s_barrier
; #define SBAR() __builtin_amdgcn_sched_barrier(0)
; __device__ __forceinline__ void finishSM(f32x16& p0, f32x16& p1, float alpha, float& l_reg, bf16x8& pa0, bf16x8& pa1, bf16x8& pa2, bf16x8& pa3) {
;     ...
;   PK4(p0, 0, pa0); PK4(p0, 8, pa1); PK4(p1, 0, pa2); PK4(p1, 8, pa3);
;     ...
; }
; __device__ __forceinline__ void qkt(f32x16& p0, f32x16& p1, const bf16* Ks, const bf16x8* qr, int r32, int hi) {
;   p0 = f32x16{}; p1 = f32x16{};
; #pragma unroll
;   for (int d0 = 0; d0 < 8; ++d0) { int cb = (d0 * 16 + hi * 8) * 2;
;     bf16x8 b0 = *reinterpret_cast<const bf16x8*>((const char*)Ks + KSWZ(r32, cb));
;     bf16x8 b1 = *reinterpret_cast<const bf16x8*>((const char*)Ks + KSWZ(32 + r32, cb));
;     p0 = __builtin_amdgcn_mfma_f32_32x32x16_bf16(b0, qr[d0], p0, 0, 0, 0);
;     p1 = __builtin_amdgcn_mfma_f32_32x32x16_bf16(b1, qr[d0], p1, 0, 0, 0); }
; }
; __device__ __forceinline__ int v_st(int k, int c) { const int kk = (k & ~0xC) | ((k & 4) << 1) | ((k & 8) >> 1); return ((kk >> 3) * 4 + (c >> 5)) * 512 + ((kk & 7) * 32 + (c & 31)) * 2; }
; __device__ __forceinline__ int v_rd_base(int lane) { return ((lane & 3) << 3) | (((lane >> 2) & 3) << 6) | (((lane >> 4) & 1) << 5) | (((lane >> 5) & 1) << 8); }
; template <int OFF> __device__ __forceinline__ s16x4 tr_read(int vb) {
;   s16x4 r; asm volatile("ds_read_b64_tr_b16 %0, %1 offset:%2" : "=&v"(r) : "v"(vb), "i"(OFF) : "memory"); return r;
; }
; template <int D0> __device__ __forceinline__ void pv_one(f32x16& od, int vb, bf16x8 pa0, bf16x8 pa1, bf16x8 pa2, bf16x8 pa3) {
;   const s16x4 l0 = tr_read<v_rd_off(D0, 0, 0)>(vb), h0 = tr_read<v_rd_off(D0, 0, 1)>(vb), l1 = tr_read<v_rd_off(D0, 1, 0)>(vb), h1 = tr_read<v_rd_off(D0, 1, 1)>(vb);
;   const s16x4 l2 = tr_read<v_rd_off(D0, 2, 0)>(vb), h2 = tr_read<v_rd_off(D0, 2, 1)>(vb), l3 = tr_read<v_rd_off(D0, 3, 0)>(vb), h3 = tr_read<v_rd_off(D0, 3, 1)>(vb);
;   asm volatile("s_waitcnt lgkmcnt(0)" ::: "memory"); SBAR();
;     ...
;   od = __builtin_amdgcn_mfma_f32_32x32x16_bf16(pa0, PK(l0, h0), od, 0, 0, 0);
;   od = __builtin_amdgcn_mfma_f32_32x32x16_bf16(pa1, PK(l1, h1), od, 0, 0, 0);
;   od = __builtin_amdgcn_mfma_f32_32x32x16_bf16(pa2, PK(l2, h2), od, 0, 0, 0);
;   od = __builtin_amdgcn_mfma_f32_32x32x16_bf16(pa3, PK(l3, h3), od, 0, 0, 0);
;     ...
; }
; __device__ __forceinline__ void pv_d0(f32x16* o, int vb, bf16x8 pa0, bf16x8 pa1, bf16x8 pa2, bf16x8 pa3) {
	v_cvt_pk_bf16_f32 v184, v128, v129
	v_add_f32_e32 v169, v169, v128
	v_add_f32_e32 v219, v219, v129
	v_cvt_pk_bf16_f32 v185, v130, v131
	v_add_f32_e32 v222, v222, v130
	v_add_f32_e32 v254, v254, v131
	v_cvt_pk_bf16_f32 v186, v132, v133
	v_add_f32_e32 v169, v169, v132
	v_add_f32_e32 v219, v219, v133
	v_cvt_pk_bf16_f32 v187, v134, v135
	v_add_f32_e32 v222, v222, v134
	v_add_f32_e32 v254, v254, v135
	v_cvt_pk_bf16_f32 v188, v136, v137
	v_add_f32_e32 v169, v169, v136
	v_add_f32_e32 v219, v219, v137
	v_permlane32_swap_b32_e32 v184, v186
	v_cvt_pk_bf16_f32 v189, v138, v139
	v_add_f32_e32 v222, v222, v138
	v_add_f32_e32 v254, v254, v139
	v_permlane32_swap_b32_e32 v185, v187
	v_cvt_pk_bf16_f32 v190, v140, v141
	v_add_f32_e32 v169, v169, v140
	v_add_f32_e32 v219, v219, v141
	v_cvt_pk_bf16_f32 v191, v142, v143
	v_add_f32_e32 v222, v222, v142
	v_add_f32_e32 v254, v254, v143
	v_cvt_pk_bf16_f32 v192, v144, v145
	v_add_f32_e32 v169, v169, v144
	v_add_f32_e32 v219, v219, v145
	v_permlane32_swap_b32_e32 v188, v190
	v_cvt_pk_bf16_f32 v193, v146, v147
	v_add_f32_e32 v222, v222, v146
	v_add_f32_e32 v254, v254, v147
	v_permlane32_swap_b32_e32 v189, v191
	v_cvt_pk_bf16_f32 v194, v148, v149
	v_add_f32_e32 v169, v169, v148
	v_add_f32_e32 v219, v219, v149
	ds_read_b64_tr_b16 v[200:201], v182 offset:49152
	ds_read_b64_tr_b16 v[202:203], v182 offset:51200
	v_cvt_pk_bf16_f32 v195, v150, v151
	v_add_f32_e32 v222, v222, v150
	v_add_f32_e32 v254, v254, v151
	ds_read_b64_tr_b16 v[204:205], v182 offset:49664
	ds_read_b64_tr_b16 v[206:207], v182 offset:51712
	v_cvt_pk_bf16_f32 v196, v152, v153
	v_add_f32_e32 v169, v169, v152
	v_add_f32_e32 v219, v219, v153
	v_permlane32_swap_b32_e32 v192, v194
	ds_read_b64_tr_b16 v[208:209], v182 offset:50176
	ds_read_b64_tr_b16 v[210:211], v182 offset:52224
	v_cvt_pk_bf16_f32 v197, v154, v155
	v_add_f32_e32 v222, v222, v154
	v_add_f32_e32 v254, v254, v155
	v_permlane32_swap_b32_e32 v193, v195
	ds_read_b64_tr_b16 v[212:213], v182 offset:50688
	ds_read_b64_tr_b16 v[214:215], v182 offset:52736
	v_cvt_pk_bf16_f32 v198, v156, v157
	v_add_f32_e32 v169, v169, v156
	v_add_f32_e32 v219, v219, v157
	ds_read_b64_tr_b16 v[230:231], v182 offset:53248
	ds_read_b64_tr_b16 v[232:233], v182 offset:55296
	v_cvt_pk_bf16_f32 v199, v158, v159
	v_add_f32_e32 v222, v222, v158
	v_add_f32_e32 v254, v254, v159
	v_permlane32_swap_b32_e32 v196, v198
	v_permlane32_swap_b32_e32 v197, v199
	s_waitcnt lgkmcnt(8)
	v_mfma_f32_32x32x16_bf16 v[0:15], v[184:187], v[200:203], v[0:15]
	ds_read_b64_tr_b16 v[234:235], v182 offset:53760
	ds_read_b64_tr_b16 v[236:237], v182 offset:55808
	s_waitcnt lgkmcnt(8)
	v_mfma_f32_32x32x16_bf16 v[48:63], v[184:187], v[204:207], v[48:63]
	ds_read_b64_tr_b16 v[238:239], v182 offset:54272
	ds_read_b64_tr_b16 v[240:241], v182 offset:56320
	s_waitcnt lgkmcnt(8)
	v_mfma_f32_32x32x16_bf16 v[32:47], v[184:187], v[208:211], v[32:47]
	ds_read_b64_tr_b16 v[242:243], v182 offset:54784
	ds_read_b64_tr_b16 v[244:245], v182 offset:56832
	s_waitcnt lgkmcnt(8)
	v_mfma_f32_32x32x16_bf16 v[16:31], v[184:187], v[212:215], v[16:31]
	ds_read_b64_tr_b16 v[200:201], v182 offset:57344
	ds_read_b64_tr_b16 v[202:203], v182 offset:59392
	s_waitcnt lgkmcnt(8)
	v_mfma_f32_32x32x16_bf16 v[0:15], v[188:191], v[230:233], v[0:15]
	ds_read_b64_tr_b16 v[204:205], v182 offset:57856
	ds_read_b64_tr_b16 v[206:207], v182 offset:59904
	s_waitcnt lgkmcnt(8)
	v_mfma_f32_32x32x16_bf16 v[48:63], v[188:191], v[234:237], v[48:63]
	ds_read_b64_tr_b16 v[208:209], v182 offset:58368
	ds_read_b64_tr_b16 v[210:211], v182 offset:60416
	s_waitcnt lgkmcnt(8)
	v_mfma_f32_32x32x16_bf16 v[32:47], v[188:191], v[238:241], v[32:47]
	ds_read_b64_tr_b16 v[212:213], v182 offset:58880
	ds_read_b64_tr_b16 v[214:215], v182 offset:60928
	s_waitcnt lgkmcnt(8)
	v_mfma_f32_32x32x16_bf16 v[16:31], v[188:191], v[242:245], v[16:31]
	ds_read_b64_tr_b16 v[230:231], v182 offset:61440
	ds_read_b64_tr_b16 v[232:233], v182 offset:63488
	s_waitcnt lgkmcnt(8)
	v_mfma_f32_32x32x16_bf16 v[0:15], v[192:195], v[200:203], v[0:15]
	ds_read_b64_tr_b16 v[234:235], v182 offset:61952
	ds_read_b64_tr_b16 v[236:237], v182 offset:64000
	s_waitcnt lgkmcnt(8)
	v_mfma_f32_32x32x16_bf16 v[48:63], v[192:195], v[204:207], v[48:63]
	ds_read_b64_tr_b16 v[238:239], v182 offset:62464
	ds_read_b64_tr_b16 v[240:241], v182 offset:64512
	s_waitcnt lgkmcnt(8)
	v_mfma_f32_32x32x16_bf16 v[32:47], v[192:195], v[208:211], v[32:47]
	ds_read_b64_tr_b16 v[242:243], v182 offset:62976
	ds_read_b64_tr_b16 v[244:245], v182 offset:65024
	s_waitcnt lgkmcnt(8)
	v_mfma_f32_32x32x16_bf16 v[16:31], v[192:195], v[212:215], v[16:31]
	s_waitcnt lgkmcnt(6)
	v_mfma_f32_32x32x16_bf16 v[0:15], v[196:199], v[230:233], v[0:15]
	s_waitcnt lgkmcnt(4)
	v_mfma_f32_32x32x16_bf16 v[48:63], v[196:199], v[234:237], v[48:63]
	s_waitcnt lgkmcnt(2)
	v_mfma_f32_32x32x16_bf16 v[32:47], v[196:199], v[238:241], v[32:47]
	s_waitcnt lgkmcnt(0)
	v_mfma_f32_32x32x16_bf16 v[16:31], v[196:199], v[242:245], v[16:31]
	s_waitcnt lgkmcnt(0)
	s_barrier
	s_setprio 0
	v_add_f32_e32 v169, v169, v219
	v_add_f32_e32 v222, v222, v254
	v_add_f32_e32 v169, v169, v222
	v_mov_b32_e32 v219, v169
	s_nop 1
	v_permlane32_swap_b32_e32 v169, v219
	v_add_f32_e32 v64, v169, v219
	v_lshlrev_b32_e32 v164, 4, v229
	v_mov_b32_e32 v165, 0
	s_and_saveexec_b64 s[0:1], s[2:3]
	ds_write_b32 v168, v64
	s_branch .LBB0_477
